# v30 + nt cache policy on the once-read w_mod / b_mod loads of the P0 modulation-vector products
# baseline (speedup 1.0000x reference)
; #define GAS __attribute__((address_space(1)))
; #define MV_LOAD(w, g8) do { _Pragma("unroll") for (int qq = 0; qq < 2; ++qq) { const GAS float* rp_ = Wu + (size_t)(8 * (g8) + 4 * qq) * DMODW; \
;             _Pragma("unroll") for (int j = 0; j < 9; ++j) w[9 * qq + j] = (rp_ + 16 * j)[loff]; } asm volatile("" ::: "memory"); } while (0)
; #define MV_COMP(w, g8) do { _Pragma("unroll") for (int qq = 0; qq < 2; ++qq) { const float a_ = svw[48 * (2 * (g8) + qq)]; \
;             _Pragma("unroll") for (int j = 0; j < 9; ++j) acc[j] = __builtin_amdgcn_mfma_f32_16x16x4f32(a_, w[9 * qq + j], acc[j], 0, 0, 0); } } while (0)
; __device__ __forceinline__ void p0_modvec(const Params& p, LAS unsigned char* lds, int tid, int lane, int wave) {
;     ...
;     for (int u = blockIdx.x; u < 2 * (DMODW / UC); u += gridDim.x) {
;         __syncthreads();
;         const int l = u / (DMODW / UC), col0 = (u % (DMODW / UC)) * UC;
;         const GAS float* Wu = (const GAS float*)uniform_ptr(p.in[IN_WMOD] + (size_t)l * D * DMODW + col0 + (size_t)(wave * 256) * DMODW);
;         const unsigned loff = (unsigned)(lk * DMODW + ln);
;         f32x4 acc[9];
; #pragma unroll
;         for (int j = 0; j < 9; ++j) acc[j] = (f32x4){0.f, 0.f, 0.f, 0.f};
;     ...
;         float wa[18], wb[18], wc[18];
;         MV_LOAD(wa, 0); MV_LOAD(wb, 1); MV_LOAD(wc, 2);
;         MV_COMP(wa, 0); MV_LOAD(wa, 3);
;         MV_COMP(wb, 1); MV_LOAD(wb, 4);
.LBB0_16:
	s_ashr_i32 s12, s67, 31
	s_load_dwordx16 s[68:83], s[0:1], 0x0
	s_lshr_b32 s12, s12, 25
	s_add_i32 s12, s67, s12
	s_ashr_i32 s58, s12, 7
	s_and_b32 s12, s12, 0xfffff80
	s_sub_i32 s12, s67, s12
	s_mul_i32 s13, s58, 0x9000000
	s_waitcnt lgkmcnt(0)
	s_add_u32 s54, s76, s13
	s_mul_hi_i32 s13, s58, 0x9000000
	s_mulk_i32 s12, 0x90
	s_addc_u32 s55, s77, s13
	s_ashr_i32 s13, s12, 31
	s_lshl_b64 s[52:53], s[12:13], 2
	s_add_u32 s12, s54, s52
	s_addc_u32 s13, s55, s53
	s_add_u32 s12, s12, s63
	s_addc_u32 s13, s13, s65
	s_barrier
	global_load_dword v14, v38, s[12:13] nt
	global_load_dword v15, v38, s[12:13] offset:64 nt
	global_load_dword v16, v38, s[12:13] offset:128 nt
	global_load_dword v17, v38, s[12:13] offset:192 nt
	global_load_dword v20, v38, s[12:13] offset:256 nt
	global_load_dword v24, v38, s[12:13] offset:320 nt
	global_load_dword v28, v38, s[12:13] offset:384 nt
	global_load_dword v32, v38, s[12:13] offset:448 nt
	global_load_dword v60, v38, s[12:13] offset:512 nt
	v_lshl_add_u64 v[2:3], s[12:13], 0, v[38:39]
	s_mov_b32 s12, 0x48000
	v_add_co_u32_e64 v4, s[12:13], s12, v2
	s_nop 1
	v_addc_co_u32_e64 v5, s[12:13], 0, v3, s[12:13]
	s_mov_b32 s12, 0x90000
	s_nop 0
	v_add_co_u32_e64 v6, s[12:13], s12, v2
	global_load_dword v64, v[4:5], off nt
	global_load_dword v65, v[4:5], off offset:64 nt
	global_load_dword v66, v[4:5], off offset:128 nt
	global_load_dword v67, v[4:5], off offset:192 nt
	global_load_dword v68, v[4:5], off offset:256 nt
	global_load_dword v69, v[4:5], off offset:320 nt
	global_load_dword v70, v[4:5], off offset:384 nt
	global_load_dword v71, v[4:5], off offset:448 nt
	global_load_dword v72, v[4:5], off offset:512 nt
	v_addc_co_u32_e64 v7, s[12:13], 0, v3, s[12:13]
	s_mov_b32 s12, 0xd8000
	s_nop 0
	v_add_co_u32_e64 v8, s[12:13], s12, v2
	s_nop 1
	v_addc_co_u32_e64 v9, s[12:13], 0, v3, s[12:13]
	s_mov_b32 s12, 0x120000
	s_nop 0
	v_add_co_u32_e64 v10, s[12:13], s12, v2
	s_nop 1
	v_addc_co_u32_e64 v11, s[12:13], 0, v3, s[12:13]
	s_mov_b32 s12, 0x168000
	s_nop 0
	v_add_co_u32_e64 v12, s[12:13], s12, v2
	s_nop 1
	v_addc_co_u32_e64 v13, s[12:13], 0, v3, s[12:13]
	s_mov_b64 s[12:13], 0x90000
	s_nop 0
	v_lshl_add_u64 v[4:5], v[2:3], 0, s[12:13]
	global_load_dword v73, v[4:5], off offset:64 nt
	global_load_dword v74, v[4:5], off offset:128 nt
	global_load_dword v75, v[4:5], off offset:192 nt
	global_load_dword v76, v[4:5], off offset:256 nt
	global_load_dword v77, v[4:5], off offset:320 nt
	global_load_dword v78, v[4:5], off offset:384 nt
	global_load_dword v79, v[4:5], off offset:448 nt
	global_load_dword v80, v[4:5], off offset:512 nt
	s_mov_b64 s[12:13], 0xd8000
	v_lshl_add_u64 v[4:5], v[2:3], 0, s[12:13]
	global_load_dword v81, v[6:7], off nt
	global_load_dword v82, v[4:5], off offset:64 nt
	global_load_dword v83, v[4:5], off offset:128 nt
	global_load_dword v84, v[4:5], off offset:192 nt
	global_load_dword v85, v[4:5], off offset:256 nt
	global_load_dword v86, v[4:5], off offset:320 nt
	global_load_dword v87, v[4:5], off offset:384 nt
	global_load_dword v88, v[4:5], off offset:448 nt
	global_load_dword v89, v[8:9], off nt
	global_load_dword v90, v[4:5], off offset:512 nt
	s_mov_b64 s[12:13], 0x120000
	v_lshl_add_u64 v[4:5], v[2:3], 0, s[12:13]
	s_mov_b64 s[12:13], 0x168000
	global_load_dword v91, v[4:5], off offset:64 nt
	global_load_dword v92, v[4:5], off offset:128 nt
	global_load_dword v93, v[4:5], off offset:192 nt
	global_load_dword v94, v[4:5], off offset:256 nt
	global_load_dword v95, v[4:5], off offset:320 nt
	global_load_dword v96, v[4:5], off offset:384 nt
	global_load_dword v97, v[4:5], off offset:448 nt
	global_load_dword v98, v[4:5], off offset:512 nt
	v_lshl_add_u64 v[4:5], v[2:3], 0, s[12:13]
	global_load_dword v99, v[10:11], off nt
	global_load_dword v100, v[4:5], off offset:64 nt
	global_load_dword v101, v[4:5], off offset:128 nt
	global_load_dword v102, v[4:5], off offset:192 nt
	global_load_dword v103, v[4:5], off offset:256 nt
	global_load_dword v104, v[4:5], off offset:320 nt
	global_load_dword v105, v[4:5], off offset:384 nt
	global_load_dword v106, v[4:5], off offset:448 nt
	global_load_dword v107, v[12:13], off nt
	global_load_dword v108, v[4:5], off offset:512 nt
	ds_read2_b32 v[36:37], v40 offset1:48
	s_mov_b32 s12, 0x1b0000
	s_waitcnt vmcnt(53) lgkmcnt(0)
	v_mfma_f32_16x16x4_f32 v[4:7], v36, v14, 0
	s_waitcnt vmcnt(52)
	v_mfma_f32_16x16x4_f32 v[8:11], v36, v15, 0
	s_waitcnt vmcnt(51)
	v_mfma_f32_16x16x4_f32 v[12:15], v36, v16, 0
	s_waitcnt vmcnt(50)
	v_mfma_f32_16x16x4_f32 v[16:19], v36, v17, 0
	s_waitcnt vmcnt(49)
	v_mfma_f32_16x16x4_f32 v[20:23], v36, v20, 0
	s_waitcnt vmcnt(48)
	v_mfma_f32_16x16x4_f32 v[24:27], v36, v24, 0
	s_waitcnt vmcnt(47)
	v_mfma_f32_16x16x4_f32 v[28:31], v36, v28, 0
	s_waitcnt vmcnt(46)
	v_mfma_f32_16x16x4_f32 v[32:35], v36, v32, 0
	s_waitcnt vmcnt(45)
	v_mfma_f32_16x16x4_f32 v[60:63], v36, v60, 0
	s_waitcnt vmcnt(44)
	v_mfma_f32_16x16x4_f32 v[4:7], v37, v64, v[4:7]
	v_add_co_u32_e64 v64, s[12:13], s12, v2
	s_waitcnt vmcnt(43)
	v_mfma_f32_16x16x4_f32 v[8:11], v37, v65, v[8:11]
	v_addc_co_u32_e64 v65, s[12:13], 0, v3, s[12:13]
	s_mov_b32 s12, 0x1f8000
	s_waitcnt vmcnt(42)
	v_mfma_f32_16x16x4_f32 v[12:15], v37, v66, v[12:15]
	v_add_co_u32_e64 v66, s[12:13], s12, v2
	s_waitcnt vmcnt(41)
	v_mfma_f32_16x16x4_f32 v[16:19], v37, v67, v[16:19]
	v_addc_co_u32_e64 v67, s[12:13], 0, v3, s[12:13]
	s_mov_b64 s[12:13], 0x1b0000
	s_waitcnt vmcnt(40)
	v_mfma_f32_16x16x4_f32 v[20:23], v37, v68, v[20:23]
	s_waitcnt vmcnt(39)
	v_mfma_f32_16x16x4_f32 v[24:27], v37, v69, v[24:27]
	s_waitcnt vmcnt(38)
	v_mfma_f32_16x16x4_f32 v[28:31], v37, v70, v[28:31]
	s_waitcnt vmcnt(37)
; #define MV_LOAD(w, g8) do { _Pragma("unroll") for (int qq = 0; qq < 2; ++qq) { const GAS float* rp_ = Wu + (size_t)(8 * (g8) + 4 * qq) * DMODW; \
;             _Pragma("unroll") for (int j = 0; j < 9; ++j) w[9 * qq + j] = (rp_ + 16 * j)[loff]; } asm volatile("" ::: "memory"); } while (0)
; #define MV_COMP(w, g8) do { _Pragma("unroll") for (int qq = 0; qq < 2; ++qq) { const float a_ = svw[48 * (2 * (g8) + qq)]; \
;             _Pragma("unroll") for (int j = 0; j < 9; ++j) acc[j] = __builtin_amdgcn_mfma_f32_16x16x4f32(a_, w[9 * qq + j], acc[j], 0, 0, 0); } } while (0)
; __device__ __forceinline__ void p0_modvec(const Params& p, LAS unsigned char* lds, int tid, int lane, int wave) {
;     ...
;         float wa[18], wb[18], wc[18];
;         MV_LOAD(wa, 0); MV_LOAD(wb, 1); MV_LOAD(wc, 2);
;         MV_COMP(wa, 0); MV_LOAD(wa, 3);
;         MV_COMP(wb, 1); MV_LOAD(wb, 4);
;         MV_COMP(wc, 2); MV_LOAD(wc, 5);
;         MV_COMP(wa, 3); MV_LOAD(wa, 6);
;         MV_COMP(wb, 4); MV_LOAD(wb, 7);
;         MV_COMP(wc, 5); MV_LOAD(wc, 8);
;         MV_COMP(wa, 6); MV_LOAD(wa, 9);
	v_mfma_f32_16x16x4_f32 v[32:35], v37, v71, v[32:35]
	s_waitcnt vmcnt(36)
	v_mfma_f32_16x16x4_f32 v[60:63], v37, v72, v[60:63]
	v_lshl_add_u64 v[36:37], v[2:3], 0, s[12:13]
	s_mov_b64 s[12:13], 0x1f8000
	global_load_dword v68, v[36:37], off offset:64 nt
	global_load_dword v69, v[36:37], off offset:128 nt
	global_load_dword v70, v[36:37], off offset:192 nt
	global_load_dword v71, v[36:37], off offset:256 nt
	global_load_dword v72, v[36:37], off offset:320 nt
	global_load_dword v109, v[36:37], off offset:384 nt
	global_load_dword v110, v[36:37], off offset:448 nt
	global_load_dword v111, v[36:37], off offset:512 nt
	v_lshl_add_u64 v[36:37], v[2:3], 0, s[12:13]
	global_load_dword v112, v[64:65], off nt
	global_load_dword v113, v[36:37], off offset:64 nt
	global_load_dword v114, v[36:37], off offset:128 nt
	global_load_dword v115, v[36:37], off offset:192 nt
	global_load_dword v116, v[36:37], off offset:256 nt
	global_load_dword v117, v[36:37], off offset:320 nt
	global_load_dword v118, v[36:37], off offset:384 nt
	global_load_dword v119, v[36:37], off offset:448 nt
	global_load_dword v120, v[66:67], off nt
	global_load_dword v121, v[36:37], off offset:512 nt
	ds_read2_b32 v[36:37], v40 offset0:96 offset1:144
	s_waitcnt vmcnt(45) lgkmcnt(0)
	v_mfma_f32_16x16x4_f32 v[4:7], v36, v81, v[4:7]
	s_mov_b32 s12, 0x240000
	v_add_co_u32_e64 v64, s[12:13], s12, v2
	s_nop 1
	v_addc_co_u32_e64 v65, s[12:13], 0, v3, s[12:13]
	s_mov_b32 s12, 0x288000
	v_mfma_f32_16x16x4_f32 v[8:11], v36, v73, v[8:11]
	v_add_co_u32_e64 v66, s[12:13], s12, v2
	s_nop 1
	v_addc_co_u32_e64 v67, s[12:13], 0, v3, s[12:13]
	s_mov_b64 s[12:13], 0x240000
	v_mfma_f32_16x16x4_f32 v[12:15], v36, v74, v[12:15]
	v_mfma_f32_16x16x4_f32 v[16:19], v36, v75, v[16:19]
	v_mfma_f32_16x16x4_f32 v[20:23], v36, v76, v[20:23]
	v_mfma_f32_16x16x4_f32 v[24:27], v36, v77, v[24:27]
	v_mfma_f32_16x16x4_f32 v[28:31], v36, v78, v[28:31]
	v_mfma_f32_16x16x4_f32 v[32:35], v36, v79, v[32:35]
	v_mfma_f32_16x16x4_f32 v[60:63], v36, v80, v[60:63]
	s_waitcnt vmcnt(37)
	v_mfma_f32_16x16x4_f32 v[4:7], v37, v89, v[4:7]
	v_mfma_f32_16x16x4_f32 v[8:11], v37, v82, v[8:11]
	v_mfma_f32_16x16x4_f32 v[12:15], v37, v83, v[12:15]
	v_mfma_f32_16x16x4_f32 v[16:19], v37, v84, v[16:19]
	v_mfma_f32_16x16x4_f32 v[20:23], v37, v85, v[20:23]
	v_mfma_f32_16x16x4_f32 v[24:27], v37, v86, v[24:27]
	v_mfma_f32_16x16x4_f32 v[28:31], v37, v87, v[28:31]
	v_mfma_f32_16x16x4_f32 v[32:35], v37, v88, v[32:35]
	s_waitcnt vmcnt(36)
	v_mfma_f32_16x16x4_f32 v[60:63], v37, v90, v[60:63]
	v_lshl_add_u64 v[36:37], v[2:3], 0, s[12:13]
	global_load_dword v73, v[36:37], off offset:64 nt
	global_load_dword v74, v[36:37], off offset:128 nt
	global_load_dword v75, v[36:37], off offset:192 nt
	global_load_dword v76, v[36:37], off offset:256 nt
	global_load_dword v77, v[36:37], off offset:320 nt
	global_load_dword v78, v[36:37], off offset:384 nt
	global_load_dword v79, v[36:37], off offset:448 nt
	global_load_dword v80, v[36:37], off offset:512 nt
	s_mov_b64 s[12:13], 0x288000
	v_lshl_add_u64 v[36:37], v[2:3], 0, s[12:13]
	global_load_dword v81, v[64:65], off nt
	global_load_dword v82, v[36:37], off offset:64 nt
	global_load_dword v83, v[36:37], off offset:128 nt
	global_load_dword v84, v[36:37], off offset:192 nt
	global_load_dword v85, v[36:37], off offset:256 nt
	global_load_dword v86, v[36:37], off offset:320 nt
	global_load_dword v87, v[36:37], off offset:384 nt
	global_load_dword v88, v[36:37], off offset:448 nt
	global_load_dword v89, v[66:67], off nt
	global_load_dword v90, v[36:37], off offset:512 nt
	ds_read2_b32 v[36:37], v40 offset0:192 offset1:240
	s_waitcnt vmcnt(45) lgkmcnt(0)
	v_mfma_f32_16x16x4_f32 v[4:7], v36, v99, v[4:7]
	s_mov_b32 s12, 0x2d0000
	v_add_co_u32_e64 v64, s[12:13], s12, v2
	s_nop 1
	v_addc_co_u32_e64 v65, s[12:13], 0, v3, s[12:13]
	s_mov_b32 s12, 0x318000
	v_mfma_f32_16x16x4_f32 v[8:11], v36, v91, v[8:11]
	v_add_co_u32_e64 v66, s[12:13], s12, v2
	s_nop 1
	v_addc_co_u32_e64 v67, s[12:13], 0, v3, s[12:13]
	s_mov_b64 s[12:13], 0x2d0000
	v_mfma_f32_16x16x4_f32 v[12:15], v36, v92, v[12:15]
	v_mfma_f32_16x16x4_f32 v[16:19], v36, v93, v[16:19]
	v_mfma_f32_16x16x4_f32 v[20:23], v36, v94, v[20:23]
	v_mfma_f32_16x16x4_f32 v[24:27], v36, v95, v[24:27]
	v_mfma_f32_16x16x4_f32 v[28:31], v36, v96, v[28:31]
	v_mfma_f32_16x16x4_f32 v[32:35], v36, v97, v[32:35]
	v_mfma_f32_16x16x4_f32 v[60:63], v36, v98, v[60:63]
	s_waitcnt vmcnt(37)
	v_mfma_f32_16x16x4_f32 v[4:7], v37, v107, v[4:7]
	v_mfma_f32_16x16x4_f32 v[8:11], v37, v100, v[8:11]
	v_mfma_f32_16x16x4_f32 v[12:15], v37, v101, v[12:15]
	v_mfma_f32_16x16x4_f32 v[16:19], v37, v102, v[16:19]
	v_mfma_f32_16x16x4_f32 v[20:23], v37, v103, v[20:23]
	v_mfma_f32_16x16x4_f32 v[24:27], v37, v104, v[24:27]
	v_mfma_f32_16x16x4_f32 v[28:31], v37, v105, v[28:31]
	v_mfma_f32_16x16x4_f32 v[32:35], v37, v106, v[32:35]
	s_waitcnt vmcnt(36)
	v_mfma_f32_16x16x4_f32 v[60:63], v37, v108, v[60:63]
	v_lshl_add_u64 v[36:37], v[2:3], 0, s[12:13]
	s_mov_b64 s[12:13], 0x318000
	global_load_dword v91, v[36:37], off offset:64 nt
	global_load_dword v92, v[36:37], off offset:128 nt
	global_load_dword v93, v[36:37], off offset:192 nt
	global_load_dword v94, v[36:37], off offset:256 nt
	global_load_dword v95, v[36:37], off offset:320 nt
	global_load_dword v96, v[36:37], off offset:384 nt
	global_load_dword v97, v[36:37], off offset:448 nt
	global_load_dword v98, v[36:37], off offset:512 nt
	v_lshl_add_u64 v[36:37], v[2:3], 0, s[12:13]
	global_load_dword v99, v[64:65], off nt
	global_load_dword v100, v[36:37], off offset:64 nt
	global_load_dword v101, v[36:37], off offset:128 nt
	global_load_dword v102, v[36:37], off offset:192 nt
	global_load_dword v103, v[36:37], off offset:256 nt
	global_load_dword v104, v[36:37], off offset:320 nt
	global_load_dword v105, v[36:37], off offset:384 nt
	global_load_dword v106, v[36:37], off offset:448 nt
	global_load_dword v107, v[66:67], off nt
	global_load_dword v108, v[36:37], off offset:512 nt
	ds_read2_b32 v[36:37], v41 offset0:32 offset1:80
	s_waitcnt vmcnt(45) lgkmcnt(0)
; #define MV_LOAD(w, g8) do { _Pragma("unroll") for (int qq = 0; qq < 2; ++qq) { const GAS float* rp_ = Wu + (size_t)(8 * (g8) + 4 * qq) * DMODW; \
;             _Pragma("unroll") for (int j = 0; j < 9; ++j) w[9 * qq + j] = (rp_ + 16 * j)[loff]; } asm volatile("" ::: "memory"); } while (0)
; #define MV_COMP(w, g8) do { _Pragma("unroll") for (int qq = 0; qq < 2; ++qq) { const float a_ = svw[48 * (2 * (g8) + qq)]; \
;             _Pragma("unroll") for (int j = 0; j < 9; ++j) acc[j] = __builtin_amdgcn_mfma_f32_16x16x4f32(a_, w[9 * qq + j], acc[j], 0, 0, 0); } } while (0)
; __device__ __forceinline__ void p0_modvec(const Params& p, LAS unsigned char* lds, int tid, int lane, int wave) {
;     ...
;         MV_COMP(wa, 3); MV_LOAD(wa, 6);
;         MV_COMP(wb, 4); MV_LOAD(wb, 7);
;         MV_COMP(wc, 5); MV_LOAD(wc, 8);
;         MV_COMP(wa, 6); MV_LOAD(wa, 9);
;         MV_COMP(wb, 7); MV_LOAD(wb, 10);
;         MV_COMP(wc, 8); MV_LOAD(wc, 11);
;         MV_COMP(wa, 9); MV_LOAD(wa, 12);
;         MV_COMP(wb, 10); MV_LOAD(wb, 13);
	v_mfma_f32_16x16x4_f32 v[4:7], v36, v112, v[4:7]
	s_mov_b32 s12, 0x360000
	v_add_co_u32_e64 v64, s[12:13], s12, v2
	s_nop 1
	v_addc_co_u32_e64 v65, s[12:13], 0, v3, s[12:13]
	s_mov_b32 s12, 0x3a8000
	v_mfma_f32_16x16x4_f32 v[8:11], v36, v68, v[8:11]
	v_add_co_u32_e64 v66, s[12:13], s12, v2
	s_nop 1
	v_addc_co_u32_e64 v67, s[12:13], 0, v3, s[12:13]
	s_mov_b64 s[12:13], 0x360000
	v_mfma_f32_16x16x4_f32 v[12:15], v36, v69, v[12:15]
	v_mfma_f32_16x16x4_f32 v[16:19], v36, v70, v[16:19]
	v_mfma_f32_16x16x4_f32 v[20:23], v36, v71, v[20:23]
	v_mfma_f32_16x16x4_f32 v[24:27], v36, v72, v[24:27]
	v_mfma_f32_16x16x4_f32 v[28:31], v36, v109, v[28:31]
	v_mfma_f32_16x16x4_f32 v[32:35], v36, v110, v[32:35]
	v_mfma_f32_16x16x4_f32 v[60:63], v36, v111, v[60:63]
	s_waitcnt vmcnt(37)
	v_mfma_f32_16x16x4_f32 v[4:7], v37, v120, v[4:7]
	v_mfma_f32_16x16x4_f32 v[8:11], v37, v113, v[8:11]
	v_mfma_f32_16x16x4_f32 v[12:15], v37, v114, v[12:15]
	v_mfma_f32_16x16x4_f32 v[16:19], v37, v115, v[16:19]
	v_mfma_f32_16x16x4_f32 v[20:23], v37, v116, v[20:23]
	v_mfma_f32_16x16x4_f32 v[24:27], v37, v117, v[24:27]
	v_mfma_f32_16x16x4_f32 v[28:31], v37, v118, v[28:31]
	v_mfma_f32_16x16x4_f32 v[32:35], v37, v119, v[32:35]
	s_waitcnt vmcnt(36)
	v_mfma_f32_16x16x4_f32 v[60:63], v37, v121, v[60:63]
	v_lshl_add_u64 v[36:37], v[2:3], 0, s[12:13]
	s_mov_b64 s[12:13], 0x3a8000
	global_load_dword v68, v[36:37], off offset:64 nt
	global_load_dword v69, v[36:37], off offset:128 nt
	global_load_dword v70, v[36:37], off offset:192 nt
	global_load_dword v71, v[36:37], off offset:256 nt
	global_load_dword v72, v[36:37], off offset:320 nt
	global_load_dword v109, v[36:37], off offset:384 nt
	global_load_dword v110, v[36:37], off offset:448 nt
	global_load_dword v111, v[36:37], off offset:512 nt
	v_lshl_add_u64 v[36:37], v[2:3], 0, s[12:13]
	global_load_dword v112, v[64:65], off nt
	global_load_dword v113, v[36:37], off offset:64 nt
	global_load_dword v114, v[36:37], off offset:128 nt
	global_load_dword v115, v[36:37], off offset:192 nt
	global_load_dword v116, v[36:37], off offset:256 nt
	global_load_dword v117, v[36:37], off offset:320 nt
	global_load_dword v118, v[36:37], off offset:384 nt
	global_load_dword v119, v[36:37], off offset:448 nt
	global_load_dword v120, v[66:67], off nt
	global_load_dword v121, v[36:37], off offset:512 nt
	ds_read2_b32 v[36:37], v41 offset0:128 offset1:176
	s_waitcnt vmcnt(45) lgkmcnt(0)
	v_mfma_f32_16x16x4_f32 v[4:7], v36, v81, v[4:7]
	s_mov_b32 s12, 0x3f0000
	v_add_co_u32_e64 v64, s[12:13], s12, v2
	s_nop 1
	v_addc_co_u32_e64 v65, s[12:13], 0, v3, s[12:13]
	s_mov_b32 s12, 0x438000
	v_mfma_f32_16x16x4_f32 v[8:11], v36, v73, v[8:11]
	v_add_co_u32_e64 v66, s[12:13], s12, v2
	s_nop 1
	v_addc_co_u32_e64 v67, s[12:13], 0, v3, s[12:13]
	s_mov_b64 s[12:13], 0x3f0000
	v_mfma_f32_16x16x4_f32 v[12:15], v36, v74, v[12:15]
	v_mfma_f32_16x16x4_f32 v[16:19], v36, v75, v[16:19]
	v_mfma_f32_16x16x4_f32 v[20:23], v36, v76, v[20:23]
	v_mfma_f32_16x16x4_f32 v[24:27], v36, v77, v[24:27]
	v_mfma_f32_16x16x4_f32 v[28:31], v36, v78, v[28:31]
	v_mfma_f32_16x16x4_f32 v[32:35], v36, v79, v[32:35]
	v_mfma_f32_16x16x4_f32 v[60:63], v36, v80, v[60:63]
	s_waitcnt vmcnt(37)
	v_mfma_f32_16x16x4_f32 v[4:7], v37, v89, v[4:7]
	v_mfma_f32_16x16x4_f32 v[8:11], v37, v82, v[8:11]
	v_mfma_f32_16x16x4_f32 v[12:15], v37, v83, v[12:15]
	v_mfma_f32_16x16x4_f32 v[16:19], v37, v84, v[16:19]
	v_mfma_f32_16x16x4_f32 v[20:23], v37, v85, v[20:23]
	v_mfma_f32_16x16x4_f32 v[24:27], v37, v86, v[24:27]
	v_mfma_f32_16x16x4_f32 v[28:31], v37, v87, v[28:31]
	v_mfma_f32_16x16x4_f32 v[32:35], v37, v88, v[32:35]
	s_waitcnt vmcnt(36)
	v_mfma_f32_16x16x4_f32 v[60:63], v37, v90, v[60:63]
	v_lshl_add_u64 v[36:37], v[2:3], 0, s[12:13]
	global_load_dword v73, v[36:37], off offset:64 nt
	global_load_dword v74, v[36:37], off offset:128 nt
	global_load_dword v75, v[36:37], off offset:192 nt
	global_load_dword v76, v[36:37], off offset:256 nt
	global_load_dword v77, v[36:37], off offset:320 nt
	global_load_dword v78, v[36:37], off offset:384 nt
	global_load_dword v79, v[36:37], off offset:448 nt
	global_load_dword v80, v[36:37], off offset:512 nt
	s_mov_b64 s[12:13], 0x438000
	v_lshl_add_u64 v[36:37], v[2:3], 0, s[12:13]
	global_load_dword v81, v[64:65], off nt
	global_load_dword v82, v[36:37], off offset:64 nt
	global_load_dword v83, v[36:37], off offset:128 nt
	global_load_dword v84, v[36:37], off offset:192 nt
	global_load_dword v85, v[36:37], off offset:256 nt
	global_load_dword v86, v[36:37], off offset:320 nt
	global_load_dword v87, v[36:37], off offset:384 nt
	global_load_dword v88, v[36:37], off offset:448 nt
	global_load_dword v89, v[66:67], off nt
	global_load_dword v90, v[36:37], off offset:512 nt
	ds_read2_b32 v[36:37], v42 offset0:96 offset1:144
	s_waitcnt vmcnt(45) lgkmcnt(0)
	v_mfma_f32_16x16x4_f32 v[4:7], v36, v99, v[4:7]
	s_mov_b32 s12, 0x480000
	v_add_co_u32_e64 v64, s[12:13], s12, v2
	s_nop 1
	v_addc_co_u32_e64 v65, s[12:13], 0, v3, s[12:13]
	s_mov_b32 s12, 0x4c8000
	v_mfma_f32_16x16x4_f32 v[8:11], v36, v91, v[8:11]
	v_add_co_u32_e64 v66, s[12:13], s12, v2
	s_nop 1
	v_addc_co_u32_e64 v67, s[12:13], 0, v3, s[12:13]
	s_mov_b64 s[12:13], 0x480000
	v_mfma_f32_16x16x4_f32 v[12:15], v36, v92, v[12:15]
	v_mfma_f32_16x16x4_f32 v[16:19], v36, v93, v[16:19]
	v_mfma_f32_16x16x4_f32 v[20:23], v36, v94, v[20:23]
	v_mfma_f32_16x16x4_f32 v[24:27], v36, v95, v[24:27]
	v_mfma_f32_16x16x4_f32 v[28:31], v36, v96, v[28:31]
	v_mfma_f32_16x16x4_f32 v[32:35], v36, v97, v[32:35]
	v_mfma_f32_16x16x4_f32 v[60:63], v36, v98, v[60:63]
	s_waitcnt vmcnt(37)
; #define MV_LOAD(w, g8) do { _Pragma("unroll") for (int qq = 0; qq < 2; ++qq) { const GAS float* rp_ = Wu + (size_t)(8 * (g8) + 4 * qq) * DMODW; \
;             _Pragma("unroll") for (int j = 0; j < 9; ++j) w[9 * qq + j] = (rp_ + 16 * j)[loff]; } asm volatile("" ::: "memory"); } while (0)
; #define MV_COMP(w, g8) do { _Pragma("unroll") for (int qq = 0; qq < 2; ++qq) { const float a_ = svw[48 * (2 * (g8) + qq)]; \
;             _Pragma("unroll") for (int j = 0; j < 9; ++j) acc[j] = __builtin_amdgcn_mfma_f32_16x16x4f32(a_, w[9 * qq + j], acc[j], 0, 0, 0); } } while (0)
; __device__ __forceinline__ void p0_modvec(const Params& p, LAS unsigned char* lds, int tid, int lane, int wave) {
;     ...
;         MV_COMP(wb, 7); MV_LOAD(wb, 10);
;         MV_COMP(wc, 8); MV_LOAD(wc, 11);
;         MV_COMP(wa, 9); MV_LOAD(wa, 12);
;         MV_COMP(wb, 10); MV_LOAD(wb, 13);
;         MV_COMP(wc, 11); MV_LOAD(wc, 14);
;         MV_COMP(wa, 12); MV_LOAD(wa, 15);
;         MV_COMP(wb, 13); MV_LOAD(wb, 16);
;         MV_COMP(wc, 14); MV_LOAD(wc, 17);
;         MV_COMP(wa, 15); MV_LOAD(wa, 18);
	v_mfma_f32_16x16x4_f32 v[4:7], v37, v107, v[4:7]
	v_mfma_f32_16x16x4_f32 v[8:11], v37, v100, v[8:11]
	v_mfma_f32_16x16x4_f32 v[12:15], v37, v101, v[12:15]
	v_mfma_f32_16x16x4_f32 v[16:19], v37, v102, v[16:19]
	v_mfma_f32_16x16x4_f32 v[20:23], v37, v103, v[20:23]
	v_mfma_f32_16x16x4_f32 v[24:27], v37, v104, v[24:27]
	v_mfma_f32_16x16x4_f32 v[28:31], v37, v105, v[28:31]
	v_mfma_f32_16x16x4_f32 v[32:35], v37, v106, v[32:35]
	s_waitcnt vmcnt(36)
	v_mfma_f32_16x16x4_f32 v[60:63], v37, v108, v[60:63]
	v_lshl_add_u64 v[36:37], v[2:3], 0, s[12:13]
	s_mov_b64 s[12:13], 0x4c8000
	global_load_dword v91, v[36:37], off offset:64 nt
	global_load_dword v92, v[36:37], off offset:128 nt
	global_load_dword v93, v[36:37], off offset:192 nt
	global_load_dword v94, v[36:37], off offset:256 nt
	global_load_dword v95, v[36:37], off offset:320 nt
	global_load_dword v96, v[36:37], off offset:384 nt
	global_load_dword v97, v[36:37], off offset:448 nt
	global_load_dword v98, v[36:37], off offset:512 nt
	v_lshl_add_u64 v[36:37], v[2:3], 0, s[12:13]
	global_load_dword v99, v[64:65], off nt
	global_load_dword v100, v[36:37], off offset:64 nt
	global_load_dword v101, v[36:37], off offset:128 nt
	global_load_dword v102, v[36:37], off offset:192 nt
	global_load_dword v103, v[36:37], off offset:256 nt
	global_load_dword v104, v[36:37], off offset:320 nt
	global_load_dword v105, v[36:37], off offset:384 nt
	global_load_dword v106, v[36:37], off offset:448 nt
	global_load_dword v107, v[66:67], off nt
	global_load_dword v108, v[36:37], off offset:512 nt
	ds_read2_b32 v[36:37], v43 offset0:64 offset1:112
	s_waitcnt vmcnt(45) lgkmcnt(0)
	v_mfma_f32_16x16x4_f32 v[4:7], v36, v112, v[4:7]
	s_mov_b32 s12, 0x510000
	v_add_co_u32_e64 v64, s[12:13], s12, v2
	s_nop 1
	v_addc_co_u32_e64 v65, s[12:13], 0, v3, s[12:13]
	s_mov_b32 s12, 0x558000
	v_mfma_f32_16x16x4_f32 v[8:11], v36, v68, v[8:11]
	v_add_co_u32_e64 v66, s[12:13], s12, v2
	s_nop 1
	v_addc_co_u32_e64 v67, s[12:13], 0, v3, s[12:13]
	s_mov_b64 s[12:13], 0x510000
	v_mfma_f32_16x16x4_f32 v[12:15], v36, v69, v[12:15]
	v_mfma_f32_16x16x4_f32 v[16:19], v36, v70, v[16:19]
	v_mfma_f32_16x16x4_f32 v[20:23], v36, v71, v[20:23]
	v_mfma_f32_16x16x4_f32 v[24:27], v36, v72, v[24:27]
	v_mfma_f32_16x16x4_f32 v[28:31], v36, v109, v[28:31]
	v_mfma_f32_16x16x4_f32 v[32:35], v36, v110, v[32:35]
	v_mfma_f32_16x16x4_f32 v[60:63], v36, v111, v[60:63]
	s_waitcnt vmcnt(37)
	v_mfma_f32_16x16x4_f32 v[4:7], v37, v120, v[4:7]
	v_mfma_f32_16x16x4_f32 v[8:11], v37, v113, v[8:11]
	v_mfma_f32_16x16x4_f32 v[12:15], v37, v114, v[12:15]
	v_mfma_f32_16x16x4_f32 v[16:19], v37, v115, v[16:19]
	v_mfma_f32_16x16x4_f32 v[20:23], v37, v116, v[20:23]
	v_mfma_f32_16x16x4_f32 v[24:27], v37, v117, v[24:27]
	v_mfma_f32_16x16x4_f32 v[28:31], v37, v118, v[28:31]
	v_mfma_f32_16x16x4_f32 v[32:35], v37, v119, v[32:35]
	s_waitcnt vmcnt(36)
	v_mfma_f32_16x16x4_f32 v[60:63], v37, v121, v[60:63]
	v_lshl_add_u64 v[36:37], v[2:3], 0, s[12:13]
	s_mov_b64 s[12:13], 0x558000
	global_load_dword v68, v[36:37], off offset:64 nt
	global_load_dword v69, v[36:37], off offset:128 nt
	global_load_dword v70, v[36:37], off offset:192 nt
	global_load_dword v71, v[36:37], off offset:256 nt
	global_load_dword v72, v[36:37], off offset:320 nt
	global_load_dword v109, v[36:37], off offset:384 nt
	global_load_dword v110, v[36:37], off offset:448 nt
	global_load_dword v111, v[36:37], off offset:512 nt
	v_lshl_add_u64 v[36:37], v[2:3], 0, s[12:13]
	global_load_dword v112, v[64:65], off nt
	global_load_dword v113, v[36:37], off offset:64 nt
	global_load_dword v114, v[36:37], off offset:128 nt
	global_load_dword v115, v[36:37], off offset:192 nt
	global_load_dword v116, v[36:37], off offset:256 nt
	global_load_dword v117, v[36:37], off offset:320 nt
	global_load_dword v118, v[36:37], off offset:384 nt
	global_load_dword v119, v[36:37], off offset:448 nt
	global_load_dword v120, v[66:67], off nt
	global_load_dword v121, v[36:37], off offset:512 nt
	ds_read2_b32 v[36:37], v43 offset0:160 offset1:208
	s_waitcnt vmcnt(45) lgkmcnt(0)
	v_mfma_f32_16x16x4_f32 v[4:7], v36, v81, v[4:7]
	s_mov_b32 s12, 0x5a0000
	v_add_co_u32_e64 v64, s[12:13], s12, v2
	s_nop 1
	v_addc_co_u32_e64 v65, s[12:13], 0, v3, s[12:13]
	s_mov_b32 s12, 0x5e8000
	v_mfma_f32_16x16x4_f32 v[8:11], v36, v73, v[8:11]
	v_add_co_u32_e64 v66, s[12:13], s12, v2
	s_nop 1
	v_addc_co_u32_e64 v67, s[12:13], 0, v3, s[12:13]
	s_mov_b64 s[12:13], 0x5a0000
	v_mfma_f32_16x16x4_f32 v[12:15], v36, v74, v[12:15]
	v_mfma_f32_16x16x4_f32 v[16:19], v36, v75, v[16:19]
	v_mfma_f32_16x16x4_f32 v[20:23], v36, v76, v[20:23]
	v_mfma_f32_16x16x4_f32 v[24:27], v36, v77, v[24:27]
	v_mfma_f32_16x16x4_f32 v[28:31], v36, v78, v[28:31]
	v_mfma_f32_16x16x4_f32 v[32:35], v36, v79, v[32:35]
	v_mfma_f32_16x16x4_f32 v[60:63], v36, v80, v[60:63]
	s_waitcnt vmcnt(37)
	v_mfma_f32_16x16x4_f32 v[4:7], v37, v89, v[4:7]
	v_mfma_f32_16x16x4_f32 v[8:11], v37, v82, v[8:11]
	v_mfma_f32_16x16x4_f32 v[12:15], v37, v83, v[12:15]
	v_mfma_f32_16x16x4_f32 v[16:19], v37, v84, v[16:19]
	v_mfma_f32_16x16x4_f32 v[20:23], v37, v85, v[20:23]
	v_mfma_f32_16x16x4_f32 v[24:27], v37, v86, v[24:27]
	v_mfma_f32_16x16x4_f32 v[28:31], v37, v87, v[28:31]
	v_mfma_f32_16x16x4_f32 v[32:35], v37, v88, v[32:35]
	s_waitcnt vmcnt(36)
; #define MV_LOAD(w, g8) do { _Pragma("unroll") for (int qq = 0; qq < 2; ++qq) { const GAS float* rp_ = Wu + (size_t)(8 * (g8) + 4 * qq) * DMODW; \
;             _Pragma("unroll") for (int j = 0; j < 9; ++j) w[9 * qq + j] = (rp_ + 16 * j)[loff]; } asm volatile("" ::: "memory"); } while (0)
; #define MV_COMP(w, g8) do { _Pragma("unroll") for (int qq = 0; qq < 2; ++qq) { const float a_ = svw[48 * (2 * (g8) + qq)]; \
;             _Pragma("unroll") for (int j = 0; j < 9; ++j) acc[j] = __builtin_amdgcn_mfma_f32_16x16x4f32(a_, w[9 * qq + j], acc[j], 0, 0, 0); } } while (0)
; __device__ __forceinline__ void p0_modvec(const Params& p, LAS unsigned char* lds, int tid, int lane, int wave) {
;     ...
;         MV_COMP(wb, 10); MV_LOAD(wb, 13);
;         MV_COMP(wc, 11); MV_LOAD(wc, 14);
;         MV_COMP(wa, 12); MV_LOAD(wa, 15);
;         MV_COMP(wb, 13); MV_LOAD(wb, 16);
;         MV_COMP(wc, 14); MV_LOAD(wc, 17);
;         MV_COMP(wa, 15); MV_LOAD(wa, 18);
;         MV_COMP(wb, 16); MV_LOAD(wb, 19);
;         MV_COMP(wc, 17); MV_LOAD(wc, 20);
;         MV_COMP(wa, 18); MV_LOAD(wa, 21);
;         MV_COMP(wb, 19); MV_LOAD(wb, 22);
;         MV_COMP(wc, 20); MV_LOAD(wc, 23);
	v_mfma_f32_16x16x4_f32 v[60:63], v37, v90, v[60:63]
	v_lshl_add_u64 v[36:37], v[2:3], 0, s[12:13]
	global_load_dword v73, v[36:37], off offset:64 nt
	global_load_dword v74, v[36:37], off offset:128 nt
	global_load_dword v75, v[36:37], off offset:192 nt
	global_load_dword v76, v[36:37], off offset:256 nt
	global_load_dword v77, v[36:37], off offset:320 nt
	global_load_dword v78, v[36:37], off offset:384 nt
	global_load_dword v79, v[36:37], off offset:448 nt
	global_load_dword v80, v[36:37], off offset:512 nt
	s_mov_b64 s[12:13], 0x5e8000
	v_lshl_add_u64 v[36:37], v[2:3], 0, s[12:13]
	global_load_dword v81, v[64:65], off nt
	global_load_dword v82, v[36:37], off offset:64 nt
	global_load_dword v83, v[36:37], off offset:128 nt
	global_load_dword v84, v[36:37], off offset:192 nt
	global_load_dword v85, v[36:37], off offset:256 nt
	global_load_dword v86, v[36:37], off offset:320 nt
	global_load_dword v87, v[36:37], off offset:384 nt
	global_load_dword v88, v[36:37], off offset:448 nt
	global_load_dword v89, v[66:67], off nt
	global_load_dword v90, v[36:37], off offset:512 nt
	ds_read2_b32 v[36:37], v44 offset1:48
	s_waitcnt vmcnt(45) lgkmcnt(0)
	v_mfma_f32_16x16x4_f32 v[4:7], v36, v99, v[4:7]
	s_mov_b32 s12, 0x630000
	v_add_co_u32_e64 v64, s[12:13], s12, v2
	s_nop 1
	v_addc_co_u32_e64 v65, s[12:13], 0, v3, s[12:13]
	s_mov_b32 s12, 0x678000
	v_mfma_f32_16x16x4_f32 v[8:11], v36, v91, v[8:11]
	v_add_co_u32_e64 v66, s[12:13], s12, v2
	s_nop 1
	v_addc_co_u32_e64 v67, s[12:13], 0, v3, s[12:13]
	s_mov_b64 s[12:13], 0x630000
	v_mfma_f32_16x16x4_f32 v[12:15], v36, v92, v[12:15]
	v_mfma_f32_16x16x4_f32 v[16:19], v36, v93, v[16:19]
	v_mfma_f32_16x16x4_f32 v[20:23], v36, v94, v[20:23]
	v_mfma_f32_16x16x4_f32 v[24:27], v36, v95, v[24:27]
	v_mfma_f32_16x16x4_f32 v[28:31], v36, v96, v[28:31]
	v_mfma_f32_16x16x4_f32 v[32:35], v36, v97, v[32:35]
	v_mfma_f32_16x16x4_f32 v[60:63], v36, v98, v[60:63]
	s_waitcnt vmcnt(37)
	v_mfma_f32_16x16x4_f32 v[4:7], v37, v107, v[4:7]
	v_mfma_f32_16x16x4_f32 v[8:11], v37, v100, v[8:11]
	v_mfma_f32_16x16x4_f32 v[12:15], v37, v101, v[12:15]
	v_mfma_f32_16x16x4_f32 v[16:19], v37, v102, v[16:19]
	v_mfma_f32_16x16x4_f32 v[20:23], v37, v103, v[20:23]
	v_mfma_f32_16x16x4_f32 v[24:27], v37, v104, v[24:27]
	v_mfma_f32_16x16x4_f32 v[28:31], v37, v105, v[28:31]
	v_mfma_f32_16x16x4_f32 v[32:35], v37, v106, v[32:35]
	s_waitcnt vmcnt(36)
	v_mfma_f32_16x16x4_f32 v[60:63], v37, v108, v[60:63]
	v_lshl_add_u64 v[36:37], v[2:3], 0, s[12:13]
	s_mov_b64 s[12:13], 0x678000
	global_load_dword v91, v[36:37], off offset:64 nt
	global_load_dword v92, v[36:37], off offset:128 nt
	global_load_dword v93, v[36:37], off offset:192 nt
	global_load_dword v94, v[36:37], off offset:256 nt
	global_load_dword v95, v[36:37], off offset:320 nt
	global_load_dword v96, v[36:37], off offset:384 nt
	global_load_dword v97, v[36:37], off offset:448 nt
	global_load_dword v98, v[36:37], off offset:512 nt
	v_lshl_add_u64 v[36:37], v[2:3], 0, s[12:13]
	global_load_dword v99, v[64:65], off nt
	global_load_dword v100, v[36:37], off offset:64 nt
	global_load_dword v101, v[36:37], off offset:128 nt
	global_load_dword v102, v[36:37], off offset:192 nt
	global_load_dword v103, v[36:37], off offset:256 nt
	global_load_dword v104, v[36:37], off offset:320 nt
	global_load_dword v105, v[36:37], off offset:384 nt
	global_load_dword v106, v[36:37], off offset:448 nt
	global_load_dword v107, v[66:67], off nt
	global_load_dword v108, v[36:37], off offset:512 nt
	ds_read2_b32 v[36:37], v44 offset0:96 offset1:144
	s_waitcnt vmcnt(45) lgkmcnt(0)
	v_mfma_f32_16x16x4_f32 v[4:7], v36, v112, v[4:7]
	s_mov_b32 s12, 0x6c0000
	v_add_co_u32_e64 v64, s[12:13], s12, v2
	s_nop 1
	v_addc_co_u32_e64 v65, s[12:13], 0, v3, s[12:13]
	s_mov_b32 s12, 0x708000
	v_mfma_f32_16x16x4_f32 v[8:11], v36, v68, v[8:11]
	v_add_co_u32_e64 v66, s[12:13], s12, v2
	s_nop 1
	v_addc_co_u32_e64 v67, s[12:13], 0, v3, s[12:13]
	s_mov_b64 s[12:13], 0x6c0000
	v_mfma_f32_16x16x4_f32 v[12:15], v36, v69, v[12:15]
	v_mfma_f32_16x16x4_f32 v[16:19], v36, v70, v[16:19]
	v_mfma_f32_16x16x4_f32 v[20:23], v36, v71, v[20:23]
	v_mfma_f32_16x16x4_f32 v[24:27], v36, v72, v[24:27]
	v_mfma_f32_16x16x4_f32 v[28:31], v36, v109, v[28:31]
	v_mfma_f32_16x16x4_f32 v[32:35], v36, v110, v[32:35]
	v_mfma_f32_16x16x4_f32 v[60:63], v36, v111, v[60:63]
	s_waitcnt vmcnt(37)
	v_mfma_f32_16x16x4_f32 v[4:7], v37, v120, v[4:7]
	v_mfma_f32_16x16x4_f32 v[8:11], v37, v113, v[8:11]
	v_mfma_f32_16x16x4_f32 v[12:15], v37, v114, v[12:15]
	v_mfma_f32_16x16x4_f32 v[16:19], v37, v115, v[16:19]
	v_mfma_f32_16x16x4_f32 v[20:23], v37, v116, v[20:23]
	v_mfma_f32_16x16x4_f32 v[24:27], v37, v117, v[24:27]
	v_mfma_f32_16x16x4_f32 v[28:31], v37, v118, v[28:31]
	v_mfma_f32_16x16x4_f32 v[32:35], v37, v119, v[32:35]
	s_waitcnt vmcnt(36)
	v_mfma_f32_16x16x4_f32 v[60:63], v37, v121, v[60:63]
	v_lshl_add_u64 v[36:37], v[2:3], 0, s[12:13]
	s_mov_b64 s[12:13], 0x708000
	global_load_dword v68, v[36:37], off offset:64 nt
	global_load_dword v69, v[36:37], off offset:128 nt
	global_load_dword v70, v[36:37], off offset:192 nt
	global_load_dword v71, v[36:37], off offset:256 nt
	global_load_dword v72, v[36:37], off offset:320 nt
	global_load_dword v109, v[36:37], off offset:384 nt
	global_load_dword v110, v[36:37], off offset:448 nt
	global_load_dword v111, v[36:37], off offset:512 nt
	v_lshl_add_u64 v[36:37], v[2:3], 0, s[12:13]
	global_load_dword v112, v[64:65], off nt
	global_load_dword v113, v[36:37], off offset:64 nt
	global_load_dword v114, v[36:37], off offset:128 nt
	global_load_dword v115, v[36:37], off offset:192 nt
	global_load_dword v116, v[36:37], off offset:256 nt
	global_load_dword v117, v[36:37], off offset:320 nt
	global_load_dword v118, v[36:37], off offset:384 nt
	global_load_dword v119, v[36:37], off offset:448 nt
	global_load_dword v120, v[66:67], off nt
	global_load_dword v121, v[36:37], off offset:512 nt
	ds_read2_b32 v[36:37], v44 offset0:192 offset1:240
	s_waitcnt vmcnt(45) lgkmcnt(0)
; #define MV_LOAD(w, g8) do { _Pragma("unroll") for (int qq = 0; qq < 2; ++qq) { const GAS float* rp_ = Wu + (size_t)(8 * (g8) + 4 * qq) * DMODW; \
;             _Pragma("unroll") for (int j = 0; j < 9; ++j) w[9 * qq + j] = (rp_ + 16 * j)[loff]; } asm volatile("" ::: "memory"); } while (0)
; #define MV_COMP(w, g8) do { _Pragma("unroll") for (int qq = 0; qq < 2; ++qq) { const float a_ = svw[48 * (2 * (g8) + qq)]; \
;             _Pragma("unroll") for (int j = 0; j < 9; ++j) acc[j] = __builtin_amdgcn_mfma_f32_16x16x4f32(a_, w[9 * qq + j], acc[j], 0, 0, 0); } } while (0)
; __device__ __forceinline__ void p0_modvec(const Params& p, LAS unsigned char* lds, int tid, int lane, int wave) {
;     ...
;         MV_COMP(wb, 13); MV_LOAD(wb, 16);
;         MV_COMP(wc, 14); MV_LOAD(wc, 17);
;         MV_COMP(wa, 15); MV_LOAD(wa, 18);
;         MV_COMP(wb, 16); MV_LOAD(wb, 19);
;         MV_COMP(wc, 17); MV_LOAD(wc, 20);
;         MV_COMP(wa, 18); MV_LOAD(wa, 21);
;         MV_COMP(wb, 19); MV_LOAD(wb, 22);
;         MV_COMP(wc, 20); MV_LOAD(wc, 23);
;         MV_COMP(wa, 21); MV_LOAD(wa, 24);
;         MV_COMP(wb, 22); MV_LOAD(wb, 25);
;         MV_COMP(wc, 23); MV_LOAD(wc, 26);
	v_mfma_f32_16x16x4_f32 v[4:7], v36, v81, v[4:7]
	s_mov_b32 s12, 0x750000
	v_add_co_u32_e64 v64, s[12:13], s12, v2
	s_nop 1
	v_addc_co_u32_e64 v65, s[12:13], 0, v3, s[12:13]
	s_mov_b32 s12, 0x798000
	v_mfma_f32_16x16x4_f32 v[8:11], v36, v73, v[8:11]
	v_add_co_u32_e64 v66, s[12:13], s12, v2
	s_nop 1
	v_addc_co_u32_e64 v67, s[12:13], 0, v3, s[12:13]
	s_mov_b64 s[12:13], 0x750000
	v_mfma_f32_16x16x4_f32 v[12:15], v36, v74, v[12:15]
	v_mfma_f32_16x16x4_f32 v[16:19], v36, v75, v[16:19]
	v_mfma_f32_16x16x4_f32 v[20:23], v36, v76, v[20:23]
	v_mfma_f32_16x16x4_f32 v[24:27], v36, v77, v[24:27]
	v_mfma_f32_16x16x4_f32 v[28:31], v36, v78, v[28:31]
	v_mfma_f32_16x16x4_f32 v[32:35], v36, v79, v[32:35]
	v_mfma_f32_16x16x4_f32 v[60:63], v36, v80, v[60:63]
	s_waitcnt vmcnt(37)
	v_mfma_f32_16x16x4_f32 v[4:7], v37, v89, v[4:7]
	v_mfma_f32_16x16x4_f32 v[8:11], v37, v82, v[8:11]
	v_mfma_f32_16x16x4_f32 v[12:15], v37, v83, v[12:15]
	v_mfma_f32_16x16x4_f32 v[16:19], v37, v84, v[16:19]
	v_mfma_f32_16x16x4_f32 v[20:23], v37, v85, v[20:23]
	v_mfma_f32_16x16x4_f32 v[24:27], v37, v86, v[24:27]
	v_mfma_f32_16x16x4_f32 v[28:31], v37, v87, v[28:31]
	v_mfma_f32_16x16x4_f32 v[32:35], v37, v88, v[32:35]
	s_waitcnt vmcnt(36)
	v_mfma_f32_16x16x4_f32 v[60:63], v37, v90, v[60:63]
	v_lshl_add_u64 v[36:37], v[2:3], 0, s[12:13]
	global_load_dword v73, v[36:37], off offset:64 nt
	global_load_dword v74, v[36:37], off offset:128 nt
	global_load_dword v75, v[36:37], off offset:192 nt
	global_load_dword v76, v[36:37], off offset:256 nt
	global_load_dword v77, v[36:37], off offset:320 nt
	global_load_dword v78, v[36:37], off offset:384 nt
	global_load_dword v79, v[36:37], off offset:448 nt
	global_load_dword v80, v[36:37], off offset:512 nt
	s_mov_b64 s[12:13], 0x798000
	v_lshl_add_u64 v[36:37], v[2:3], 0, s[12:13]
	global_load_dword v81, v[64:65], off nt
	global_load_dword v82, v[36:37], off offset:64 nt
	global_load_dword v83, v[36:37], off offset:128 nt
	global_load_dword v84, v[36:37], off offset:192 nt
	global_load_dword v85, v[36:37], off offset:256 nt
	global_load_dword v86, v[36:37], off offset:320 nt
	global_load_dword v87, v[36:37], off offset:384 nt
	global_load_dword v88, v[36:37], off offset:448 nt
	global_load_dword v89, v[66:67], off nt
	global_load_dword v90, v[36:37], off offset:512 nt
	ds_read2_b32 v[36:37], v45 offset0:32 offset1:80
	s_waitcnt vmcnt(45) lgkmcnt(0)
	v_mfma_f32_16x16x4_f32 v[4:7], v36, v99, v[4:7]
	s_mov_b32 s12, 0x7e0000
	v_add_co_u32_e64 v64, s[12:13], s12, v2
	s_nop 1
	v_addc_co_u32_e64 v65, s[12:13], 0, v3, s[12:13]
	s_mov_b32 s12, 0x828000
	v_mfma_f32_16x16x4_f32 v[8:11], v36, v91, v[8:11]
	v_add_co_u32_e64 v66, s[12:13], s12, v2
	s_nop 1
	v_addc_co_u32_e64 v67, s[12:13], 0, v3, s[12:13]
	s_mov_b64 s[12:13], 0x7e0000
	v_mfma_f32_16x16x4_f32 v[12:15], v36, v92, v[12:15]
	v_mfma_f32_16x16x4_f32 v[16:19], v36, v93, v[16:19]
	v_mfma_f32_16x16x4_f32 v[20:23], v36, v94, v[20:23]
	v_mfma_f32_16x16x4_f32 v[24:27], v36, v95, v[24:27]
	v_mfma_f32_16x16x4_f32 v[28:31], v36, v96, v[28:31]
	v_mfma_f32_16x16x4_f32 v[32:35], v36, v97, v[32:35]
	v_mfma_f32_16x16x4_f32 v[60:63], v36, v98, v[60:63]
	s_waitcnt vmcnt(37)
	v_mfma_f32_16x16x4_f32 v[4:7], v37, v107, v[4:7]
	v_mfma_f32_16x16x4_f32 v[8:11], v37, v100, v[8:11]
	v_mfma_f32_16x16x4_f32 v[12:15], v37, v101, v[12:15]
	v_mfma_f32_16x16x4_f32 v[16:19], v37, v102, v[16:19]
	v_mfma_f32_16x16x4_f32 v[20:23], v37, v103, v[20:23]
	v_mfma_f32_16x16x4_f32 v[24:27], v37, v104, v[24:27]
	v_mfma_f32_16x16x4_f32 v[28:31], v37, v105, v[28:31]
	v_mfma_f32_16x16x4_f32 v[32:35], v37, v106, v[32:35]
	s_waitcnt vmcnt(36)
	v_mfma_f32_16x16x4_f32 v[60:63], v37, v108, v[60:63]
	v_lshl_add_u64 v[36:37], v[2:3], 0, s[12:13]
	s_mov_b64 s[12:13], 0x828000
	global_load_dword v91, v[36:37], off offset:64 nt
	global_load_dword v92, v[36:37], off offset:128 nt
	global_load_dword v93, v[36:37], off offset:192 nt
	global_load_dword v94, v[36:37], off offset:256 nt
	global_load_dword v95, v[36:37], off offset:320 nt
	global_load_dword v96, v[36:37], off offset:384 nt
	global_load_dword v97, v[36:37], off offset:448 nt
	global_load_dword v98, v[36:37], off offset:512 nt
	v_lshl_add_u64 v[36:37], v[2:3], 0, s[12:13]
	global_load_dword v99, v[64:65], off nt
	global_load_dword v100, v[36:37], off offset:64 nt
	global_load_dword v101, v[36:37], off offset:128 nt
	global_load_dword v102, v[36:37], off offset:192 nt
	global_load_dword v103, v[36:37], off offset:256 nt
	global_load_dword v104, v[36:37], off offset:320 nt
	global_load_dword v105, v[36:37], off offset:384 nt
	global_load_dword v106, v[36:37], off offset:448 nt
	global_load_dword v107, v[66:67], off nt
	global_load_dword v108, v[36:37], off offset:512 nt
	ds_read2_b32 v[36:37], v45 offset0:128 offset1:176
	s_waitcnt vmcnt(45) lgkmcnt(0)
	v_mfma_f32_16x16x4_f32 v[4:7], v36, v112, v[4:7]
	s_mov_b32 s12, 0x870000
	v_add_co_u32_e64 v64, s[12:13], s12, v2
	s_nop 1
	v_addc_co_u32_e64 v65, s[12:13], 0, v3, s[12:13]
	s_mov_b32 s12, 0x8b8000
	v_mfma_f32_16x16x4_f32 v[8:11], v36, v68, v[8:11]
	v_add_co_u32_e64 v66, s[12:13], s12, v2
	s_nop 1
	v_addc_co_u32_e64 v67, s[12:13], 0, v3, s[12:13]
	s_mov_b64 s[12:13], 0x870000
	v_mfma_f32_16x16x4_f32 v[12:15], v36, v69, v[12:15]
	v_mfma_f32_16x16x4_f32 v[16:19], v36, v70, v[16:19]
	v_mfma_f32_16x16x4_f32 v[20:23], v36, v71, v[20:23]
	v_mfma_f32_16x16x4_f32 v[24:27], v36, v72, v[24:27]
	v_mfma_f32_16x16x4_f32 v[28:31], v36, v109, v[28:31]
	v_mfma_f32_16x16x4_f32 v[32:35], v36, v110, v[32:35]
	v_mfma_f32_16x16x4_f32 v[60:63], v36, v111, v[60:63]
	s_waitcnt vmcnt(37)
; #define MV_LOAD(w, g8) do { _Pragma("unroll") for (int qq = 0; qq < 2; ++qq) { const GAS float* rp_ = Wu + (size_t)(8 * (g8) + 4 * qq) * DMODW; \
;             _Pragma("unroll") for (int j = 0; j < 9; ++j) w[9 * qq + j] = (rp_ + 16 * j)[loff]; } asm volatile("" ::: "memory"); } while (0)
; #define MV_COMP(w, g8) do { _Pragma("unroll") for (int qq = 0; qq < 2; ++qq) { const float a_ = svw[48 * (2 * (g8) + qq)]; \
;             _Pragma("unroll") for (int j = 0; j < 9; ++j) acc[j] = __builtin_amdgcn_mfma_f32_16x16x4f32(a_, w[9 * qq + j], acc[j], 0, 0, 0); } } while (0)
; __device__ __forceinline__ void p0_modvec(const Params& p, LAS unsigned char* lds, int tid, int lane, int wave) {
;     ...
;         float wa[18], wb[18], wc[18];
;         MV_LOAD(wa, 0); MV_LOAD(wb, 1); MV_LOAD(wc, 2);
;         MV_COMP(wa, 0); MV_LOAD(wa, 3);
;         MV_COMP(wb, 1); MV_LOAD(wb, 4);
;         MV_COMP(wc, 2); MV_LOAD(wc, 5);
;         MV_COMP(wa, 3); MV_LOAD(wa, 6);
;         MV_COMP(wb, 4); MV_LOAD(wb, 7);
;         MV_COMP(wc, 5); MV_LOAD(wc, 8);
;         MV_COMP(wa, 6); MV_LOAD(wa, 9);
;         MV_COMP(wb, 7); MV_LOAD(wb, 10);
;         MV_COMP(wc, 8); MV_LOAD(wc, 11);
;         MV_COMP(wa, 9); MV_LOAD(wa, 12);
;         MV_COMP(wb, 10); MV_LOAD(wb, 13);
;         MV_COMP(wc, 11); MV_LOAD(wc, 14);
;         MV_COMP(wa, 12); MV_LOAD(wa, 15);
;         MV_COMP(wb, 13); MV_LOAD(wb, 16);
;         MV_COMP(wc, 14); MV_LOAD(wc, 17);
;         MV_COMP(wa, 15); MV_LOAD(wa, 18);
;         MV_COMP(wb, 16); MV_LOAD(wb, 19);
;         MV_COMP(wc, 17); MV_LOAD(wc, 20);
;         MV_COMP(wa, 18); MV_LOAD(wa, 21);
;         MV_COMP(wb, 19); MV_LOAD(wb, 22);
;         MV_COMP(wc, 20); MV_LOAD(wc, 23);
;         MV_COMP(wa, 21); MV_LOAD(wa, 24);
;         MV_COMP(wb, 22); MV_LOAD(wb, 25);
;         MV_COMP(wc, 23); MV_LOAD(wc, 26);
;         MV_COMP(wa, 24); MV_LOAD(wa, 27);
;         MV_COMP(wb, 25); MV_LOAD(wb, 28);
;         MV_COMP(wc, 26); MV_LOAD(wc, 29);
;         MV_COMP(wa, 27); MV_LOAD(wa, 30);
;         MV_COMP(wb, 28); MV_LOAD(wb, 31);
;         MV_COMP(wc, 29);
;         MV_COMP(wa, 30);
;         MV_COMP(wb, 31);
	v_mfma_f32_16x16x4_f32 v[4:7], v37, v120, v[4:7]
	v_mfma_f32_16x16x4_f32 v[8:11], v37, v113, v[8:11]
	v_mfma_f32_16x16x4_f32 v[12:15], v37, v114, v[12:15]
	v_mfma_f32_16x16x4_f32 v[16:19], v37, v115, v[16:19]
	v_mfma_f32_16x16x4_f32 v[20:23], v37, v116, v[20:23]
	v_mfma_f32_16x16x4_f32 v[24:27], v37, v117, v[24:27]
	v_mfma_f32_16x16x4_f32 v[28:31], v37, v118, v[28:31]
	v_mfma_f32_16x16x4_f32 v[32:35], v37, v119, v[32:35]
	s_waitcnt vmcnt(36)
	v_mfma_f32_16x16x4_f32 v[60:63], v37, v121, v[60:63]
	v_lshl_add_u64 v[36:37], v[2:3], 0, s[12:13]
	s_mov_b64 s[12:13], 0x8b8000
	global_load_dword v68, v[36:37], off offset:64 nt
	global_load_dword v69, v[36:37], off offset:128 nt
	global_load_dword v70, v[36:37], off offset:192 nt
	global_load_dword v71, v[36:37], off offset:256 nt
	global_load_dword v72, v[36:37], off offset:320 nt
	global_load_dword v109, v[36:37], off offset:384 nt
	global_load_dword v110, v[36:37], off offset:448 nt
	global_load_dword v111, v[36:37], off offset:512 nt
	v_lshl_add_u64 v[36:37], v[2:3], 0, s[12:13]
	global_load_dword v112, v[64:65], off nt
	global_load_dword v113, v[36:37], off offset:64 nt
	global_load_dword v114, v[36:37], off offset:128 nt
	global_load_dword v115, v[36:37], off offset:192 nt
	global_load_dword v116, v[36:37], off offset:256 nt
	global_load_dword v117, v[36:37], off offset:320 nt
	global_load_dword v118, v[36:37], off offset:384 nt
	global_load_dword v119, v[36:37], off offset:448 nt
	global_load_dword v120, v[66:67], off nt
	global_load_dword v121, v[36:37], off offset:512 nt
	ds_read2_b32 v[36:37], v46 offset0:96 offset1:144
	s_waitcnt vmcnt(45) lgkmcnt(0)
	v_mfma_f32_16x16x4_f32 v[4:7], v36, v81, v[4:7]
	s_mov_b32 s12, 0x900000
	v_add_co_u32_e64 v64, s[12:13], s12, v2
	s_nop 1
	v_addc_co_u32_e64 v65, s[12:13], 0, v3, s[12:13]
	s_mov_b32 s12, 0x948000
	v_mfma_f32_16x16x4_f32 v[8:11], v36, v73, v[8:11]
	v_add_co_u32_e64 v66, s[12:13], s12, v2
	s_nop 1
	v_addc_co_u32_e64 v67, s[12:13], 0, v3, s[12:13]
	s_mov_b64 s[12:13], 0x900000
	v_mfma_f32_16x16x4_f32 v[12:15], v36, v74, v[12:15]
	v_mfma_f32_16x16x4_f32 v[16:19], v36, v75, v[16:19]
	v_mfma_f32_16x16x4_f32 v[20:23], v36, v76, v[20:23]
	v_mfma_f32_16x16x4_f32 v[24:27], v36, v77, v[24:27]
	v_mfma_f32_16x16x4_f32 v[28:31], v36, v78, v[28:31]
	v_mfma_f32_16x16x4_f32 v[32:35], v36, v79, v[32:35]
	v_mfma_f32_16x16x4_f32 v[60:63], v36, v80, v[60:63]
	s_waitcnt vmcnt(37)
	v_mfma_f32_16x16x4_f32 v[4:7], v37, v89, v[4:7]
	v_mfma_f32_16x16x4_f32 v[8:11], v37, v82, v[8:11]
	v_mfma_f32_16x16x4_f32 v[12:15], v37, v83, v[12:15]
	v_mfma_f32_16x16x4_f32 v[16:19], v37, v84, v[16:19]
	v_mfma_f32_16x16x4_f32 v[20:23], v37, v85, v[20:23]
	v_mfma_f32_16x16x4_f32 v[24:27], v37, v86, v[24:27]
	v_mfma_f32_16x16x4_f32 v[28:31], v37, v87, v[28:31]
	v_mfma_f32_16x16x4_f32 v[32:35], v37, v88, v[32:35]
	s_waitcnt vmcnt(36)
	v_mfma_f32_16x16x4_f32 v[60:63], v37, v90, v[60:63]
	v_lshl_add_u64 v[36:37], v[2:3], 0, s[12:13]
	global_load_dword v73, v[36:37], off offset:64 nt
	global_load_dword v74, v[36:37], off offset:128 nt
	global_load_dword v75, v[36:37], off offset:192 nt
	global_load_dword v76, v[36:37], off offset:256 nt
	global_load_dword v77, v[36:37], off offset:320 nt
	global_load_dword v78, v[36:37], off offset:384 nt
	global_load_dword v79, v[36:37], off offset:448 nt
	global_load_dword v80, v[36:37], off offset:512 nt
	s_mov_b64 s[12:13], 0x948000
	v_lshl_add_u64 v[36:37], v[2:3], 0, s[12:13]
	global_load_dword v81, v[64:65], off nt
	global_load_dword v82, v[36:37], off offset:64 nt
	global_load_dword v83, v[36:37], off offset:128 nt
	global_load_dword v84, v[36:37], off offset:192 nt
	global_load_dword v85, v[36:37], off offset:256 nt
	global_load_dword v86, v[36:37], off offset:320 nt
	global_load_dword v87, v[36:37], off offset:384 nt
	global_load_dword v88, v[36:37], off offset:448 nt
	global_load_dword v89, v[66:67], off nt
	global_load_dword v90, v[36:37], off offset:512 nt
	ds_read2_b32 v[36:37], v47 offset0:64 offset1:112
	s_waitcnt vmcnt(45) lgkmcnt(0)
	v_mfma_f32_16x16x4_f32 v[4:7], v36, v99, v[4:7]
	s_mov_b32 s12, 0x990000
	v_add_co_u32_e64 v64, s[12:13], s12, v2
	s_nop 1
	v_addc_co_u32_e64 v65, s[12:13], 0, v3, s[12:13]
	s_mov_b32 s12, 0x9d8000
	v_mfma_f32_16x16x4_f32 v[8:11], v36, v91, v[8:11]
	v_add_co_u32_e64 v66, s[12:13], s12, v2
	s_nop 1
	v_addc_co_u32_e64 v67, s[12:13], 0, v3, s[12:13]
	s_mov_b64 s[12:13], 0x990000
	v_mfma_f32_16x16x4_f32 v[12:15], v36, v92, v[12:15]
	v_mfma_f32_16x16x4_f32 v[16:19], v36, v93, v[16:19]
	v_mfma_f32_16x16x4_f32 v[20:23], v36, v94, v[20:23]
	v_mfma_f32_16x16x4_f32 v[24:27], v36, v95, v[24:27]
	v_mfma_f32_16x16x4_f32 v[28:31], v36, v96, v[28:31]
	v_mfma_f32_16x16x4_f32 v[32:35], v36, v97, v[32:35]
	v_mfma_f32_16x16x4_f32 v[60:63], v36, v98, v[60:63]
	s_waitcnt vmcnt(37)
	v_mfma_f32_16x16x4_f32 v[4:7], v37, v107, v[4:7]
	v_mfma_f32_16x16x4_f32 v[8:11], v37, v100, v[8:11]
	v_mfma_f32_16x16x4_f32 v[12:15], v37, v101, v[12:15]
	v_mfma_f32_16x16x4_f32 v[16:19], v37, v102, v[16:19]
	v_mfma_f32_16x16x4_f32 v[20:23], v37, v103, v[20:23]
	v_mfma_f32_16x16x4_f32 v[24:27], v37, v104, v[24:27]
	v_mfma_f32_16x16x4_f32 v[28:31], v37, v105, v[28:31]
	v_mfma_f32_16x16x4_f32 v[32:35], v37, v106, v[32:35]
	s_waitcnt vmcnt(36)
; #define MV_LOAD(w, g8) do { _Pragma("unroll") for (int qq = 0; qq < 2; ++qq) { const GAS float* rp_ = Wu + (size_t)(8 * (g8) + 4 * qq) * DMODW; \
;             _Pragma("unroll") for (int j = 0; j < 9; ++j) w[9 * qq + j] = (rp_ + 16 * j)[loff]; } asm volatile("" ::: "memory"); } while (0)
; #define MV_COMP(w, g8) do { _Pragma("unroll") for (int qq = 0; qq < 2; ++qq) { const float a_ = svw[48 * (2 * (g8) + qq)]; \
;             _Pragma("unroll") for (int j = 0; j < 9; ++j) acc[j] = __builtin_amdgcn_mfma_f32_16x16x4f32(a_, w[9 * qq + j], acc[j], 0, 0, 0); } } while (0)
; __device__ __forceinline__ void p0_modvec(const Params& p, LAS unsigned char* lds, int tid, int lane, int wave) {
;     ...
;         float wa[18], wb[18], wc[18];
;         MV_LOAD(wa, 0); MV_LOAD(wb, 1); MV_LOAD(wc, 2);
;         MV_COMP(wa, 0); MV_LOAD(wa, 3);
;         MV_COMP(wb, 1); MV_LOAD(wb, 4);
;         MV_COMP(wc, 2); MV_LOAD(wc, 5);
;         MV_COMP(wa, 3); MV_LOAD(wa, 6);
;         MV_COMP(wb, 4); MV_LOAD(wb, 7);
;         MV_COMP(wc, 5); MV_LOAD(wc, 8);
;         MV_COMP(wa, 6); MV_LOAD(wa, 9);
;         MV_COMP(wb, 7); MV_LOAD(wb, 10);
;         MV_COMP(wc, 8); MV_LOAD(wc, 11);
;         MV_COMP(wa, 9); MV_LOAD(wa, 12);
;         MV_COMP(wb, 10); MV_LOAD(wb, 13);
;         MV_COMP(wc, 11); MV_LOAD(wc, 14);
;         MV_COMP(wa, 12); MV_LOAD(wa, 15);
;         MV_COMP(wb, 13); MV_LOAD(wb, 16);
;         MV_COMP(wc, 14); MV_LOAD(wc, 17);
;         MV_COMP(wa, 15); MV_LOAD(wa, 18);
;         MV_COMP(wb, 16); MV_LOAD(wb, 19);
;         MV_COMP(wc, 17); MV_LOAD(wc, 20);
;         MV_COMP(wa, 18); MV_LOAD(wa, 21);
;         MV_COMP(wb, 19); MV_LOAD(wb, 22);
;         MV_COMP(wc, 20); MV_LOAD(wc, 23);
;         MV_COMP(wa, 21); MV_LOAD(wa, 24);
;         MV_COMP(wb, 22); MV_LOAD(wb, 25);
;         MV_COMP(wc, 23); MV_LOAD(wc, 26);
;         MV_COMP(wa, 24); MV_LOAD(wa, 27);
;         MV_COMP(wb, 25); MV_LOAD(wb, 28);
;         MV_COMP(wc, 26); MV_LOAD(wc, 29);
;         MV_COMP(wa, 27); MV_LOAD(wa, 30);
;         MV_COMP(wb, 28); MV_LOAD(wb, 31);
;         MV_COMP(wc, 29);
;         MV_COMP(wa, 30);
;         MV_COMP(wb, 31);
	v_mfma_f32_16x16x4_f32 v[60:63], v37, v108, v[60:63]
	v_lshl_add_u64 v[36:37], v[2:3], 0, s[12:13]
	s_mov_b64 s[12:13], 0x9d8000
	global_load_dword v91, v[36:37], off offset:64 nt
	global_load_dword v92, v[36:37], off offset:128 nt
	global_load_dword v93, v[36:37], off offset:192 nt
	global_load_dword v94, v[36:37], off offset:256 nt
	global_load_dword v95, v[36:37], off offset:320 nt
	global_load_dword v96, v[36:37], off offset:384 nt
	global_load_dword v97, v[36:37], off offset:448 nt
	global_load_dword v98, v[36:37], off offset:512 nt
	v_lshl_add_u64 v[36:37], v[2:3], 0, s[12:13]
	global_load_dword v99, v[64:65], off nt
	global_load_dword v100, v[36:37], off offset:64 nt
	global_load_dword v101, v[36:37], off offset:128 nt
	global_load_dword v102, v[36:37], off offset:192 nt
	global_load_dword v103, v[36:37], off offset:256 nt
	global_load_dword v104, v[36:37], off offset:320 nt
	global_load_dword v105, v[36:37], off offset:384 nt
	global_load_dword v106, v[36:37], off offset:448 nt
	global_load_dword v107, v[66:67], off nt
	global_load_dword v108, v[36:37], off offset:512 nt
	ds_read2_b32 v[36:37], v47 offset0:160 offset1:208
	s_waitcnt vmcnt(45) lgkmcnt(0)
	v_mfma_f32_16x16x4_f32 v[4:7], v36, v112, v[4:7]
	s_mov_b32 s12, 0xa20000
	v_add_co_u32_e64 v64, s[12:13], s12, v2
	s_nop 1
	v_addc_co_u32_e64 v65, s[12:13], 0, v3, s[12:13]
	s_mov_b32 s12, 0xa68000
	v_mfma_f32_16x16x4_f32 v[8:11], v36, v68, v[8:11]
	v_add_co_u32_e64 v66, s[12:13], s12, v2
	s_nop 1
	v_addc_co_u32_e64 v67, s[12:13], 0, v3, s[12:13]
	s_mov_b64 s[12:13], 0xa20000
	v_mfma_f32_16x16x4_f32 v[12:15], v36, v69, v[12:15]
	v_mfma_f32_16x16x4_f32 v[16:19], v36, v70, v[16:19]
	v_mfma_f32_16x16x4_f32 v[20:23], v36, v71, v[20:23]
	v_mfma_f32_16x16x4_f32 v[24:27], v36, v72, v[24:27]
	v_mfma_f32_16x16x4_f32 v[28:31], v36, v109, v[28:31]
	v_mfma_f32_16x16x4_f32 v[32:35], v36, v110, v[32:35]
	v_mfma_f32_16x16x4_f32 v[60:63], v36, v111, v[60:63]
	s_waitcnt vmcnt(37)
	v_mfma_f32_16x16x4_f32 v[4:7], v37, v120, v[4:7]
	v_mfma_f32_16x16x4_f32 v[8:11], v37, v113, v[8:11]
	v_mfma_f32_16x16x4_f32 v[12:15], v37, v114, v[12:15]
	v_mfma_f32_16x16x4_f32 v[16:19], v37, v115, v[16:19]
	v_mfma_f32_16x16x4_f32 v[20:23], v37, v116, v[20:23]
	v_mfma_f32_16x16x4_f32 v[24:27], v37, v117, v[24:27]
	v_mfma_f32_16x16x4_f32 v[28:31], v37, v118, v[28:31]
	v_mfma_f32_16x16x4_f32 v[32:35], v37, v119, v[32:35]
	s_waitcnt vmcnt(36)
	v_mfma_f32_16x16x4_f32 v[60:63], v37, v121, v[60:63]
	v_lshl_add_u64 v[36:37], v[2:3], 0, s[12:13]
	s_mov_b64 s[12:13], 0xa68000
	global_load_dword v68, v[36:37], off offset:64 nt
	global_load_dword v69, v[36:37], off offset:128 nt
	global_load_dword v70, v[36:37], off offset:192 nt
	global_load_dword v71, v[36:37], off offset:256 nt
	global_load_dword v72, v[36:37], off offset:320 nt
	global_load_dword v109, v[36:37], off offset:384 nt
	global_load_dword v110, v[36:37], off offset:448 nt
	global_load_dword v111, v[36:37], off offset:512 nt
	v_lshl_add_u64 v[36:37], v[2:3], 0, s[12:13]
	global_load_dword v112, v[64:65], off nt
	global_load_dword v113, v[36:37], off offset:64 nt
	global_load_dword v114, v[36:37], off offset:128 nt
	global_load_dword v115, v[36:37], off offset:192 nt
	global_load_dword v116, v[36:37], off offset:256 nt
	global_load_dword v117, v[36:37], off offset:320 nt
	global_load_dword v118, v[36:37], off offset:384 nt
	global_load_dword v119, v[36:37], off offset:448 nt
	global_load_dword v120, v[66:67], off nt
	global_load_dword v121, v[36:37], off offset:512 nt
	ds_read2_b32 v[36:37], v48 offset1:48
	s_waitcnt vmcnt(45) lgkmcnt(0)
	v_mfma_f32_16x16x4_f32 v[4:7], v36, v81, v[4:7]
	s_mov_b32 s12, 0xab0000
	v_add_co_u32_e64 v64, s[12:13], s12, v2
	s_nop 1
	v_addc_co_u32_e64 v65, s[12:13], 0, v3, s[12:13]
	s_mov_b32 s12, 0xaf8000
	v_mfma_f32_16x16x4_f32 v[8:11], v36, v73, v[8:11]
	v_add_co_u32_e64 v66, s[12:13], s12, v2
	s_nop 1
	v_addc_co_u32_e64 v67, s[12:13], 0, v3, s[12:13]
	s_mov_b64 s[12:13], 0xab0000
	v_mfma_f32_16x16x4_f32 v[12:15], v36, v74, v[12:15]
	v_mfma_f32_16x16x4_f32 v[16:19], v36, v75, v[16:19]
	v_mfma_f32_16x16x4_f32 v[20:23], v36, v76, v[20:23]
	v_mfma_f32_16x16x4_f32 v[24:27], v36, v77, v[24:27]
	v_mfma_f32_16x16x4_f32 v[28:31], v36, v78, v[28:31]
	v_mfma_f32_16x16x4_f32 v[32:35], v36, v79, v[32:35]
	v_mfma_f32_16x16x4_f32 v[60:63], v36, v80, v[60:63]
	s_waitcnt vmcnt(37)
	v_mfma_f32_16x16x4_f32 v[4:7], v37, v89, v[4:7]
	v_mfma_f32_16x16x4_f32 v[8:11], v37, v82, v[8:11]
	v_mfma_f32_16x16x4_f32 v[12:15], v37, v83, v[12:15]
	v_mfma_f32_16x16x4_f32 v[16:19], v37, v84, v[16:19]
	v_mfma_f32_16x16x4_f32 v[20:23], v37, v85, v[20:23]
	v_mfma_f32_16x16x4_f32 v[24:27], v37, v86, v[24:27]
	v_mfma_f32_16x16x4_f32 v[28:31], v37, v87, v[28:31]
	v_mfma_f32_16x16x4_f32 v[32:35], v37, v88, v[32:35]
	s_waitcnt vmcnt(36)
	v_mfma_f32_16x16x4_f32 v[60:63], v37, v90, v[60:63]
	v_lshl_add_u64 v[36:37], v[2:3], 0, s[12:13]
	global_load_dword v73, v[36:37], off offset:64 nt
	global_load_dword v74, v[36:37], off offset:128 nt
	global_load_dword v75, v[36:37], off offset:192 nt
	global_load_dword v76, v[36:37], off offset:256 nt
	global_load_dword v77, v[36:37], off offset:320 nt
	global_load_dword v78, v[36:37], off offset:384 nt
	global_load_dword v79, v[36:37], off offset:448 nt
	global_load_dword v80, v[36:37], off offset:512 nt
	s_mov_b64 s[12:13], 0xaf8000
	v_lshl_add_u64 v[36:37], v[2:3], 0, s[12:13]
	global_load_dword v81, v[64:65], off nt
	global_load_dword v82, v[36:37], off offset:64 nt
	global_load_dword v83, v[36:37], off offset:128 nt
	global_load_dword v84, v[36:37], off offset:192 nt
	global_load_dword v85, v[36:37], off offset:256 nt
	global_load_dword v86, v[36:37], off offset:320 nt
	global_load_dword v87, v[36:37], off offset:384 nt
	global_load_dword v88, v[36:37], off offset:448 nt
	global_load_dword v89, v[66:67], off nt
	global_load_dword v90, v[36:37], off offset:512 nt
	ds_read2_b32 v[36:37], v48 offset0:96 offset1:144
	s_waitcnt vmcnt(45) lgkmcnt(0)
; #define MV_LOAD(w, g8) do { _Pragma("unroll") for (int qq = 0; qq < 2; ++qq) { const GAS float* rp_ = Wu + (size_t)(8 * (g8) + 4 * qq) * DMODW; \
;             _Pragma("unroll") for (int j = 0; j < 9; ++j) w[9 * qq + j] = (rp_ + 16 * j)[loff]; } asm volatile("" ::: "memory"); } while (0)
; #define MV_COMP(w, g8) do { _Pragma("unroll") for (int qq = 0; qq < 2; ++qq) { const float a_ = svw[48 * (2 * (g8) + qq)]; \
;             _Pragma("unroll") for (int j = 0; j < 9; ++j) acc[j] = __builtin_amdgcn_mfma_f32_16x16x4f32(a_, w[9 * qq + j], acc[j], 0, 0, 0); } } while (0)
; __device__ __forceinline__ void p0_modvec(const Params& p, LAS unsigned char* lds, int tid, int lane, int wave) {
;     ...
;         float wa[18], wb[18], wc[18];
;         MV_LOAD(wa, 0); MV_LOAD(wb, 1); MV_LOAD(wc, 2);
;         MV_COMP(wa, 0); MV_LOAD(wa, 3);
;         MV_COMP(wb, 1); MV_LOAD(wb, 4);
;         MV_COMP(wc, 2); MV_LOAD(wc, 5);
;         MV_COMP(wa, 3); MV_LOAD(wa, 6);
;         MV_COMP(wb, 4); MV_LOAD(wb, 7);
;         MV_COMP(wc, 5); MV_LOAD(wc, 8);
;         MV_COMP(wa, 6); MV_LOAD(wa, 9);
;         MV_COMP(wb, 7); MV_LOAD(wb, 10);
;         MV_COMP(wc, 8); MV_LOAD(wc, 11);
;         MV_COMP(wa, 9); MV_LOAD(wa, 12);
;         MV_COMP(wb, 10); MV_LOAD(wb, 13);
;         MV_COMP(wc, 11); MV_LOAD(wc, 14);
;         MV_COMP(wa, 12); MV_LOAD(wa, 15);
;         MV_COMP(wb, 13); MV_LOAD(wb, 16);
;         MV_COMP(wc, 14); MV_LOAD(wc, 17);
;         MV_COMP(wa, 15); MV_LOAD(wa, 18);
;         MV_COMP(wb, 16); MV_LOAD(wb, 19);
;         MV_COMP(wc, 17); MV_LOAD(wc, 20);
;         MV_COMP(wa, 18); MV_LOAD(wa, 21);
;         MV_COMP(wb, 19); MV_LOAD(wb, 22);
;         MV_COMP(wc, 20); MV_LOAD(wc, 23);
;         MV_COMP(wa, 21); MV_LOAD(wa, 24);
;         MV_COMP(wb, 22); MV_LOAD(wb, 25);
;         MV_COMP(wc, 23); MV_LOAD(wc, 26);
;         MV_COMP(wa, 24); MV_LOAD(wa, 27);
;         MV_COMP(wb, 25); MV_LOAD(wb, 28);
;         MV_COMP(wc, 26); MV_LOAD(wc, 29);
;         MV_COMP(wa, 27); MV_LOAD(wa, 30);
;         MV_COMP(wb, 28); MV_LOAD(wb, 31);
;         MV_COMP(wc, 29);
;         MV_COMP(wa, 30);
;         MV_COMP(wb, 31);
	v_mfma_f32_16x16x4_f32 v[4:7], v36, v99, v[4:7]
	s_mov_b32 s12, 0xb40000
	v_add_co_u32_e64 v64, s[12:13], s12, v2
	s_nop 1
	v_addc_co_u32_e64 v65, s[12:13], 0, v3, s[12:13]
	s_mov_b32 s12, 0xb88000
	v_mfma_f32_16x16x4_f32 v[8:11], v36, v91, v[8:11]
	v_add_co_u32_e64 v66, s[12:13], s12, v2
	s_nop 1
	v_addc_co_u32_e64 v67, s[12:13], 0, v3, s[12:13]
	s_mov_b64 s[12:13], 0xb40000
	v_mfma_f32_16x16x4_f32 v[12:15], v36, v92, v[12:15]
	v_mfma_f32_16x16x4_f32 v[16:19], v36, v93, v[16:19]
	v_mfma_f32_16x16x4_f32 v[20:23], v36, v94, v[20:23]
	v_mfma_f32_16x16x4_f32 v[24:27], v36, v95, v[24:27]
	v_mfma_f32_16x16x4_f32 v[28:31], v36, v96, v[28:31]
	v_mfma_f32_16x16x4_f32 v[32:35], v36, v97, v[32:35]
	v_mfma_f32_16x16x4_f32 v[60:63], v36, v98, v[60:63]
	s_waitcnt vmcnt(37)
	v_mfma_f32_16x16x4_f32 v[4:7], v37, v107, v[4:7]
	v_mfma_f32_16x16x4_f32 v[8:11], v37, v100, v[8:11]
	v_mfma_f32_16x16x4_f32 v[12:15], v37, v101, v[12:15]
	v_mfma_f32_16x16x4_f32 v[16:19], v37, v102, v[16:19]
	v_mfma_f32_16x16x4_f32 v[20:23], v37, v103, v[20:23]
	v_mfma_f32_16x16x4_f32 v[24:27], v37, v104, v[24:27]
	v_mfma_f32_16x16x4_f32 v[28:31], v37, v105, v[28:31]
	v_mfma_f32_16x16x4_f32 v[32:35], v37, v106, v[32:35]
	s_waitcnt vmcnt(36)
	v_mfma_f32_16x16x4_f32 v[60:63], v37, v108, v[60:63]
	v_lshl_add_u64 v[36:37], v[2:3], 0, s[12:13]
	s_mov_b64 s[12:13], 0xb88000
	global_load_dword v91, v[36:37], off offset:64 nt
	global_load_dword v92, v[36:37], off offset:128 nt
	global_load_dword v93, v[36:37], off offset:192 nt
	global_load_dword v94, v[36:37], off offset:256 nt
	global_load_dword v95, v[36:37], off offset:320 nt
	global_load_dword v96, v[36:37], off offset:384 nt
	global_load_dword v97, v[36:37], off offset:448 nt
	global_load_dword v98, v[36:37], off offset:512 nt
	v_lshl_add_u64 v[36:37], v[2:3], 0, s[12:13]
	global_load_dword v99, v[64:65], off nt
	global_load_dword v100, v[36:37], off offset:64 nt
	global_load_dword v101, v[36:37], off offset:128 nt
	global_load_dword v102, v[36:37], off offset:192 nt
	global_load_dword v103, v[36:37], off offset:256 nt
	global_load_dword v104, v[36:37], off offset:320 nt
	global_load_dword v105, v[36:37], off offset:384 nt
	global_load_dword v106, v[36:37], off offset:448 nt
	global_load_dword v107, v[66:67], off nt
	global_load_dword v108, v[36:37], off offset:512 nt
	ds_read2_b32 v[36:37], v48 offset0:192 offset1:240
	s_waitcnt vmcnt(45) lgkmcnt(0)
	v_mfma_f32_16x16x4_f32 v[4:7], v36, v112, v[4:7]
	s_mov_b32 s12, 0xbd0000
	v_add_co_u32_e64 v64, s[12:13], s12, v2
	s_nop 1
	v_addc_co_u32_e64 v65, s[12:13], 0, v3, s[12:13]
	s_mov_b32 s12, 0xc18000
	v_mfma_f32_16x16x4_f32 v[8:11], v36, v68, v[8:11]
	v_add_co_u32_e64 v66, s[12:13], s12, v2
	s_nop 1
	v_addc_co_u32_e64 v67, s[12:13], 0, v3, s[12:13]
	s_mov_b64 s[12:13], 0xbd0000
	v_mfma_f32_16x16x4_f32 v[12:15], v36, v69, v[12:15]
	v_mfma_f32_16x16x4_f32 v[16:19], v36, v70, v[16:19]
	v_mfma_f32_16x16x4_f32 v[20:23], v36, v71, v[20:23]
	v_mfma_f32_16x16x4_f32 v[24:27], v36, v72, v[24:27]
	v_mfma_f32_16x16x4_f32 v[28:31], v36, v109, v[28:31]
	v_mfma_f32_16x16x4_f32 v[32:35], v36, v110, v[32:35]
	v_mfma_f32_16x16x4_f32 v[60:63], v36, v111, v[60:63]
	s_waitcnt vmcnt(37)
	v_mfma_f32_16x16x4_f32 v[4:7], v37, v120, v[4:7]
	v_mfma_f32_16x16x4_f32 v[8:11], v37, v113, v[8:11]
	v_mfma_f32_16x16x4_f32 v[12:15], v37, v114, v[12:15]
	v_mfma_f32_16x16x4_f32 v[16:19], v37, v115, v[16:19]
	v_mfma_f32_16x16x4_f32 v[20:23], v37, v116, v[20:23]
	v_mfma_f32_16x16x4_f32 v[24:27], v37, v117, v[24:27]
	v_mfma_f32_16x16x4_f32 v[28:31], v37, v118, v[28:31]
	v_mfma_f32_16x16x4_f32 v[32:35], v37, v119, v[32:35]
	s_waitcnt vmcnt(36)
	v_mfma_f32_16x16x4_f32 v[60:63], v37, v121, v[60:63]
	v_lshl_add_u64 v[36:37], v[2:3], 0, s[12:13]
	s_mov_b64 s[12:13], 0xc18000
	global_load_dword v68, v[36:37], off offset:64 nt
	global_load_dword v69, v[36:37], off offset:128 nt
	global_load_dword v70, v[36:37], off offset:192 nt
	global_load_dword v71, v[36:37], off offset:256 nt
	global_load_dword v72, v[36:37], off offset:320 nt
	global_load_dword v109, v[36:37], off offset:384 nt
	global_load_dword v110, v[36:37], off offset:448 nt
	global_load_dword v111, v[36:37], off offset:512 nt
	v_lshl_add_u64 v[36:37], v[2:3], 0, s[12:13]
	global_load_dword v112, v[64:65], off nt
	global_load_dword v113, v[36:37], off offset:64 nt
	global_load_dword v114, v[36:37], off offset:128 nt
	global_load_dword v115, v[36:37], off offset:192 nt
	global_load_dword v116, v[36:37], off offset:256 nt
	global_load_dword v117, v[36:37], off offset:320 nt
	global_load_dword v118, v[36:37], off offset:384 nt
	global_load_dword v119, v[36:37], off offset:448 nt
	global_load_dword v120, v[66:67], off nt
	global_load_dword v121, v[36:37], off offset:512 nt
	ds_read2_b32 v[36:37], v49 offset0:32 offset1:80
	s_waitcnt vmcnt(45) lgkmcnt(0)
	v_mfma_f32_16x16x4_f32 v[4:7], v36, v81, v[4:7]
	s_mov_b32 s12, 0xc60000
	v_add_co_u32_e64 v64, s[12:13], s12, v2
	s_nop 1
	v_addc_co_u32_e64 v65, s[12:13], 0, v3, s[12:13]
	s_mov_b32 s12, 0xca8000
	v_mfma_f32_16x16x4_f32 v[8:11], v36, v73, v[8:11]
	v_add_co_u32_e64 v66, s[12:13], s12, v2
	s_nop 1
	v_addc_co_u32_e64 v67, s[12:13], 0, v3, s[12:13]
	s_mov_b64 s[12:13], 0xc60000
	v_mfma_f32_16x16x4_f32 v[12:15], v36, v74, v[12:15]
	v_mfma_f32_16x16x4_f32 v[16:19], v36, v75, v[16:19]
	v_mfma_f32_16x16x4_f32 v[20:23], v36, v76, v[20:23]
	v_mfma_f32_16x16x4_f32 v[24:27], v36, v77, v[24:27]
	v_mfma_f32_16x16x4_f32 v[28:31], v36, v78, v[28:31]
	v_mfma_f32_16x16x4_f32 v[32:35], v36, v79, v[32:35]
	v_mfma_f32_16x16x4_f32 v[60:63], v36, v80, v[60:63]
	s_waitcnt vmcnt(37)
; #define MV_LOAD(w, g8) do { _Pragma("unroll") for (int qq = 0; qq < 2; ++qq) { const GAS float* rp_ = Wu + (size_t)(8 * (g8) + 4 * qq) * DMODW; \
;             _Pragma("unroll") for (int j = 0; j < 9; ++j) w[9 * qq + j] = (rp_ + 16 * j)[loff]; } asm volatile("" ::: "memory"); } while (0)
; #define MV_COMP(w, g8) do { _Pragma("unroll") for (int qq = 0; qq < 2; ++qq) { const float a_ = svw[48 * (2 * (g8) + qq)]; \
;             _Pragma("unroll") for (int j = 0; j < 9; ++j) acc[j] = __builtin_amdgcn_mfma_f32_16x16x4f32(a_, w[9 * qq + j], acc[j], 0, 0, 0); } } while (0)
; __device__ __forceinline__ void p0_modvec(const Params& p, LAS unsigned char* lds, int tid, int lane, int wave) {
;     ...
;         float wa[18], wb[18], wc[18];
;         MV_LOAD(wa, 0); MV_LOAD(wb, 1); MV_LOAD(wc, 2);
;         MV_COMP(wa, 0); MV_LOAD(wa, 3);
;         MV_COMP(wb, 1); MV_LOAD(wb, 4);
;         MV_COMP(wc, 2); MV_LOAD(wc, 5);
;         MV_COMP(wa, 3); MV_LOAD(wa, 6);
;         MV_COMP(wb, 4); MV_LOAD(wb, 7);
;         MV_COMP(wc, 5); MV_LOAD(wc, 8);
;         MV_COMP(wa, 6); MV_LOAD(wa, 9);
;         MV_COMP(wb, 7); MV_LOAD(wb, 10);
;         MV_COMP(wc, 8); MV_LOAD(wc, 11);
;         MV_COMP(wa, 9); MV_LOAD(wa, 12);
;         MV_COMP(wb, 10); MV_LOAD(wb, 13);
;         MV_COMP(wc, 11); MV_LOAD(wc, 14);
;         MV_COMP(wa, 12); MV_LOAD(wa, 15);
;         MV_COMP(wb, 13); MV_LOAD(wb, 16);
;         MV_COMP(wc, 14); MV_LOAD(wc, 17);
;         MV_COMP(wa, 15); MV_LOAD(wa, 18);
;         MV_COMP(wb, 16); MV_LOAD(wb, 19);
;         MV_COMP(wc, 17); MV_LOAD(wc, 20);
;         MV_COMP(wa, 18); MV_LOAD(wa, 21);
;         MV_COMP(wb, 19); MV_LOAD(wb, 22);
;         MV_COMP(wc, 20); MV_LOAD(wc, 23);
;         MV_COMP(wa, 21); MV_LOAD(wa, 24);
;         MV_COMP(wb, 22); MV_LOAD(wb, 25);
;         MV_COMP(wc, 23); MV_LOAD(wc, 26);
;         MV_COMP(wa, 24); MV_LOAD(wa, 27);
;         MV_COMP(wb, 25); MV_LOAD(wb, 28);
;         MV_COMP(wc, 26); MV_LOAD(wc, 29);
;         MV_COMP(wa, 27); MV_LOAD(wa, 30);
;         MV_COMP(wb, 28); MV_LOAD(wb, 31);
;         MV_COMP(wc, 29);
;         MV_COMP(wa, 30);
;         MV_COMP(wb, 31);
	v_mfma_f32_16x16x4_f32 v[4:7], v37, v89, v[4:7]
	v_mfma_f32_16x16x4_f32 v[8:11], v37, v82, v[8:11]
	v_mfma_f32_16x16x4_f32 v[12:15], v37, v83, v[12:15]
	v_mfma_f32_16x16x4_f32 v[16:19], v37, v84, v[16:19]
	v_mfma_f32_16x16x4_f32 v[20:23], v37, v85, v[20:23]
	v_mfma_f32_16x16x4_f32 v[24:27], v37, v86, v[24:27]
	v_mfma_f32_16x16x4_f32 v[28:31], v37, v87, v[28:31]
	v_mfma_f32_16x16x4_f32 v[32:35], v37, v88, v[32:35]
	s_waitcnt vmcnt(36)
	v_mfma_f32_16x16x4_f32 v[60:63], v37, v90, v[60:63]
	v_lshl_add_u64 v[36:37], v[2:3], 0, s[12:13]
	global_load_dword v73, v[36:37], off offset:64 nt
	global_load_dword v74, v[36:37], off offset:128 nt
	global_load_dword v75, v[36:37], off offset:192 nt
	global_load_dword v76, v[36:37], off offset:256 nt
	global_load_dword v77, v[36:37], off offset:320 nt
	global_load_dword v78, v[36:37], off offset:384 nt
	global_load_dword v79, v[36:37], off offset:448 nt
	global_load_dword v80, v[36:37], off offset:512 nt
	v_lshl_add_u64 v[36:37], v[2:3], 0, s[2:3]
	global_load_dword v81, v[64:65], off nt
	global_load_dword v82, v[36:37], off offset:64 nt
	global_load_dword v83, v[36:37], off offset:128 nt
	global_load_dword v84, v[36:37], off offset:192 nt
	global_load_dword v85, v[36:37], off offset:256 nt
	global_load_dword v86, v[36:37], off offset:320 nt
	global_load_dword v87, v[36:37], off offset:384 nt
	global_load_dword v88, v[36:37], off offset:448 nt
	global_load_dword v89, v[66:67], off nt
	global_load_dword v90, v[36:37], off offset:512 nt
	ds_read2_b32 v[36:37], v49 offset0:128 offset1:176
	s_mov_b32 s12, 0xcf0000
	s_waitcnt vmcnt(45) lgkmcnt(0)
	v_mfma_f32_16x16x4_f32 v[4:7], v36, v99, v[4:7]
	v_add_co_u32_e64 v64, s[12:13], s12, v2
	s_nop 1
	v_addc_co_u32_e64 v65, s[12:13], 0, v3, s[12:13]
	s_mov_b32 s12, 0xd38000
	s_nop 0
	v_add_co_u32_e64 v66, s[12:13], s12, v2
	v_mfma_f32_16x16x4_f32 v[8:11], v36, v91, v[8:11]
	s_nop 0
	v_addc_co_u32_e64 v67, s[12:13], 0, v3, s[12:13]
	s_mov_b32 s12, 0xd80000
	v_mfma_f32_16x16x4_f32 v[12:15], v36, v92, v[12:15]
	v_mfma_f32_16x16x4_f32 v[16:19], v36, v93, v[16:19]
	v_mfma_f32_16x16x4_f32 v[20:23], v36, v94, v[20:23]
	v_mfma_f32_16x16x4_f32 v[24:27], v36, v95, v[24:27]
	v_mfma_f32_16x16x4_f32 v[28:31], v36, v96, v[28:31]
	v_mfma_f32_16x16x4_f32 v[32:35], v36, v97, v[32:35]
	v_mfma_f32_16x16x4_f32 v[60:63], v36, v98, v[60:63]
	s_waitcnt vmcnt(37)
	v_mfma_f32_16x16x4_f32 v[4:7], v37, v107, v[4:7]
	v_mfma_f32_16x16x4_f32 v[8:11], v37, v100, v[8:11]
	v_mfma_f32_16x16x4_f32 v[12:15], v37, v101, v[12:15]
	v_mfma_f32_16x16x4_f32 v[16:19], v37, v102, v[16:19]
	v_mfma_f32_16x16x4_f32 v[20:23], v37, v103, v[20:23]
	v_mfma_f32_16x16x4_f32 v[24:27], v37, v104, v[24:27]
	v_mfma_f32_16x16x4_f32 v[28:31], v37, v105, v[28:31]
	v_mfma_f32_16x16x4_f32 v[32:35], v37, v106, v[32:35]
	s_waitcnt vmcnt(36)
	v_mfma_f32_16x16x4_f32 v[60:63], v37, v108, v[60:63]
	v_lshl_add_u64 v[36:37], v[2:3], 0, s[14:15]
	global_load_dword v91, v[36:37], off offset:64 nt
	global_load_dword v92, v[36:37], off offset:128 nt
	global_load_dword v93, v[36:37], off offset:192 nt
	global_load_dword v94, v[36:37], off offset:256 nt
	global_load_dword v95, v[36:37], off offset:320 nt
	global_load_dword v96, v[36:37], off offset:384 nt
	global_load_dword v97, v[36:37], off offset:448 nt
	global_load_dword v98, v[36:37], off offset:512 nt
	v_lshl_add_u64 v[36:37], v[2:3], 0, s[16:17]
	global_load_dword v99, v[64:65], off nt
	global_load_dword v100, v[36:37], off offset:64 nt
	global_load_dword v101, v[36:37], off offset:128 nt
	global_load_dword v102, v[36:37], off offset:192 nt
	global_load_dword v103, v[36:37], off offset:256 nt
	global_load_dword v104, v[36:37], off offset:320 nt
	global_load_dword v105, v[36:37], off offset:384 nt
	global_load_dword v106, v[36:37], off offset:448 nt
	global_load_dword v107, v[66:67], off nt
	global_load_dword v108, v[36:37], off offset:512 nt
	ds_read2_b32 v[36:37], v50 offset0:96 offset1:144
	v_add_co_u32_e64 v64, s[12:13], s12, v2
	s_waitcnt vmcnt(45) lgkmcnt(0)
	v_mfma_f32_16x16x4_f32 v[4:7], v36, v112, v[4:7]
	v_addc_co_u32_e64 v65, s[12:13], 0, v3, s[12:13]
	s_mov_b32 s12, 0xdc8000
	s_nop 0
	v_add_co_u32_e64 v66, s[12:13], s12, v2
	s_nop 1
	v_addc_co_u32_e64 v67, s[12:13], 0, v3, s[12:13]
	v_mfma_f32_16x16x4_f32 v[8:11], v36, v68, v[8:11]
	s_mov_b32 s12, 0xe10000
	v_mfma_f32_16x16x4_f32 v[12:15], v36, v69, v[12:15]
	v_mfma_f32_16x16x4_f32 v[16:19], v36, v70, v[16:19]
	v_mfma_f32_16x16x4_f32 v[20:23], v36, v71, v[20:23]
	v_mfma_f32_16x16x4_f32 v[24:27], v36, v72, v[24:27]
	v_mfma_f32_16x16x4_f32 v[28:31], v36, v109, v[28:31]
	v_mfma_f32_16x16x4_f32 v[32:35], v36, v110, v[32:35]
	v_mfma_f32_16x16x4_f32 v[60:63], v36, v111, v[60:63]
	s_waitcnt vmcnt(37)
	v_mfma_f32_16x16x4_f32 v[4:7], v37, v120, v[4:7]
	v_mfma_f32_16x16x4_f32 v[8:11], v37, v113, v[8:11]
	v_mfma_f32_16x16x4_f32 v[12:15], v37, v114, v[12:15]
	v_mfma_f32_16x16x4_f32 v[16:19], v37, v115, v[16:19]
	v_mfma_f32_16x16x4_f32 v[20:23], v37, v116, v[20:23]
	v_mfma_f32_16x16x4_f32 v[24:27], v37, v117, v[24:27]
	v_mfma_f32_16x16x4_f32 v[28:31], v37, v118, v[28:31]
	v_mfma_f32_16x16x4_f32 v[32:35], v37, v119, v[32:35]
	s_waitcnt vmcnt(36)
; #define MV_LOAD(w, g8) do { _Pragma("unroll") for (int qq = 0; qq < 2; ++qq) { const GAS float* rp_ = Wu + (size_t)(8 * (g8) + 4 * qq) * DMODW; \
;             _Pragma("unroll") for (int j = 0; j < 9; ++j) w[9 * qq + j] = (rp_ + 16 * j)[loff]; } asm volatile("" ::: "memory"); } while (0)
; #define MV_COMP(w, g8) do { _Pragma("unroll") for (int qq = 0; qq < 2; ++qq) { const float a_ = svw[48 * (2 * (g8) + qq)]; \
;             _Pragma("unroll") for (int j = 0; j < 9; ++j) acc[j] = __builtin_amdgcn_mfma_f32_16x16x4f32(a_, w[9 * qq + j], acc[j], 0, 0, 0); } } while (0)
; __device__ __forceinline__ void p0_modvec(const Params& p, LAS unsigned char* lds, int tid, int lane, int wave) {
;     ...
;         float wa[18], wb[18], wc[18];
;         MV_LOAD(wa, 0); MV_LOAD(wb, 1); MV_LOAD(wc, 2);
;         MV_COMP(wa, 0); MV_LOAD(wa, 3);
;         MV_COMP(wb, 1); MV_LOAD(wb, 4);
;         MV_COMP(wc, 2); MV_LOAD(wc, 5);
;         MV_COMP(wa, 3); MV_LOAD(wa, 6);
;         MV_COMP(wb, 4); MV_LOAD(wb, 7);
;         MV_COMP(wc, 5); MV_LOAD(wc, 8);
;         MV_COMP(wa, 6); MV_LOAD(wa, 9);
;         MV_COMP(wb, 7); MV_LOAD(wb, 10);
;         MV_COMP(wc, 8); MV_LOAD(wc, 11);
;         MV_COMP(wa, 9); MV_LOAD(wa, 12);
;         MV_COMP(wb, 10); MV_LOAD(wb, 13);
;         MV_COMP(wc, 11); MV_LOAD(wc, 14);
;         MV_COMP(wa, 12); MV_LOAD(wa, 15);
;         MV_COMP(wb, 13); MV_LOAD(wb, 16);
;         MV_COMP(wc, 14); MV_LOAD(wc, 17);
;         MV_COMP(wa, 15); MV_LOAD(wa, 18);
;         MV_COMP(wb, 16); MV_LOAD(wb, 19);
;         MV_COMP(wc, 17); MV_LOAD(wc, 20);
;         MV_COMP(wa, 18); MV_LOAD(wa, 21);
;         MV_COMP(wb, 19); MV_LOAD(wb, 22);
;         MV_COMP(wc, 20); MV_LOAD(wc, 23);
;         MV_COMP(wa, 21); MV_LOAD(wa, 24);
;         MV_COMP(wb, 22); MV_LOAD(wb, 25);
;         MV_COMP(wc, 23); MV_LOAD(wc, 26);
;         MV_COMP(wa, 24); MV_LOAD(wa, 27);
;         MV_COMP(wb, 25); MV_LOAD(wb, 28);
;         MV_COMP(wc, 26); MV_LOAD(wc, 29);
;         MV_COMP(wa, 27); MV_LOAD(wa, 30);
;         MV_COMP(wb, 28); MV_LOAD(wb, 31);
;         MV_COMP(wc, 29);
;         MV_COMP(wa, 30);
;         MV_COMP(wb, 31);
	v_mfma_f32_16x16x4_f32 v[60:63], v37, v121, v[60:63]
	v_lshl_add_u64 v[36:37], v[2:3], 0, s[18:19]
	global_load_dword v68, v[36:37], off offset:64 nt
	global_load_dword v69, v[36:37], off offset:128 nt
	global_load_dword v70, v[36:37], off offset:192 nt
	global_load_dword v71, v[36:37], off offset:256 nt
	global_load_dword v72, v[36:37], off offset:320 nt
	global_load_dword v109, v[36:37], off offset:384 nt
	global_load_dword v110, v[36:37], off offset:448 nt
	global_load_dword v111, v[36:37], off offset:512 nt
	v_lshl_add_u64 v[36:37], v[2:3], 0, s[20:21]
	global_load_dword v112, v[64:65], off nt
	global_load_dword v113, v[36:37], off offset:64 nt
	global_load_dword v114, v[36:37], off offset:128 nt
	global_load_dword v115, v[36:37], off offset:192 nt
	global_load_dword v116, v[36:37], off offset:256 nt
	global_load_dword v117, v[36:37], off offset:320 nt
	global_load_dword v118, v[36:37], off offset:384 nt
	global_load_dword v119, v[36:37], off offset:448 nt
	global_load_dword v120, v[66:67], off nt
	global_load_dword v121, v[36:37], off offset:512 nt
	ds_read2_b32 v[36:37], v51 offset0:64 offset1:112
	v_add_co_u32_e64 v64, s[12:13], s12, v2
	s_waitcnt vmcnt(45) lgkmcnt(0)
	v_mfma_f32_16x16x4_f32 v[4:7], v36, v81, v[4:7]
	v_addc_co_u32_e64 v65, s[12:13], 0, v3, s[12:13]
	s_mov_b32 s12, 0xe58000
	s_nop 0
	v_add_co_u32_e64 v66, s[12:13], s12, v2
	s_nop 1
	v_addc_co_u32_e64 v67, s[12:13], 0, v3, s[12:13]
	v_mfma_f32_16x16x4_f32 v[8:11], v36, v73, v[8:11]
	s_mov_b32 s12, 0xea0000
	v_mfma_f32_16x16x4_f32 v[12:15], v36, v74, v[12:15]
	v_mfma_f32_16x16x4_f32 v[16:19], v36, v75, v[16:19]
	v_mfma_f32_16x16x4_f32 v[20:23], v36, v76, v[20:23]
	v_mfma_f32_16x16x4_f32 v[24:27], v36, v77, v[24:27]
	v_mfma_f32_16x16x4_f32 v[28:31], v36, v78, v[28:31]
	v_mfma_f32_16x16x4_f32 v[32:35], v36, v79, v[32:35]
	v_mfma_f32_16x16x4_f32 v[60:63], v36, v80, v[60:63]
	s_waitcnt vmcnt(37)
	v_mfma_f32_16x16x4_f32 v[4:7], v37, v89, v[4:7]
	v_mfma_f32_16x16x4_f32 v[8:11], v37, v82, v[8:11]
	v_mfma_f32_16x16x4_f32 v[12:15], v37, v83, v[12:15]
	v_mfma_f32_16x16x4_f32 v[16:19], v37, v84, v[16:19]
	v_mfma_f32_16x16x4_f32 v[20:23], v37, v85, v[20:23]
	v_mfma_f32_16x16x4_f32 v[24:27], v37, v86, v[24:27]
	v_mfma_f32_16x16x4_f32 v[28:31], v37, v87, v[28:31]
	v_mfma_f32_16x16x4_f32 v[32:35], v37, v88, v[32:35]
	s_waitcnt vmcnt(36)
	v_mfma_f32_16x16x4_f32 v[60:63], v37, v90, v[60:63]
	v_lshl_add_u64 v[36:37], v[2:3], 0, s[22:23]
	global_load_dword v73, v[36:37], off offset:64 nt
	global_load_dword v74, v[36:37], off offset:128 nt
	global_load_dword v75, v[36:37], off offset:192 nt
	global_load_dword v76, v[36:37], off offset:256 nt
	global_load_dword v77, v[36:37], off offset:320 nt
	global_load_dword v78, v[36:37], off offset:384 nt
	global_load_dword v79, v[36:37], off offset:448 nt
	global_load_dword v80, v[36:37], off offset:512 nt
	v_lshl_add_u64 v[36:37], v[2:3], 0, s[24:25]
	global_load_dword v81, v[64:65], off nt
	global_load_dword v82, v[36:37], off offset:64 nt
	global_load_dword v83, v[36:37], off offset:128 nt
	global_load_dword v84, v[36:37], off offset:192 nt
	global_load_dword v85, v[36:37], off offset:256 nt
	global_load_dword v86, v[36:37], off offset:320 nt
	global_load_dword v87, v[36:37], off offset:384 nt
	global_load_dword v88, v[36:37], off offset:448 nt
	global_load_dword v89, v[66:67], off nt
	global_load_dword v90, v[36:37], off offset:512 nt
	ds_read2_b32 v[36:37], v51 offset0:160 offset1:208
	v_add_co_u32_e64 v64, s[12:13], s12, v2
	s_waitcnt vmcnt(45) lgkmcnt(0)
	v_mfma_f32_16x16x4_f32 v[4:7], v36, v99, v[4:7]
	v_addc_co_u32_e64 v65, s[12:13], 0, v3, s[12:13]
	s_mov_b32 s12, 0xee8000
	s_nop 0
	v_add_co_u32_e64 v66, s[12:13], s12, v2
	s_nop 1
	v_addc_co_u32_e64 v67, s[12:13], 0, v3, s[12:13]
	v_mfma_f32_16x16x4_f32 v[8:11], v36, v91, v[8:11]
	s_mov_b32 s12, 0xf30000
	v_mfma_f32_16x16x4_f32 v[12:15], v36, v92, v[12:15]
	v_mfma_f32_16x16x4_f32 v[16:19], v36, v93, v[16:19]
	v_mfma_f32_16x16x4_f32 v[20:23], v36, v94, v[20:23]
	v_mfma_f32_16x16x4_f32 v[24:27], v36, v95, v[24:27]
	v_mfma_f32_16x16x4_f32 v[28:31], v36, v96, v[28:31]
	v_mfma_f32_16x16x4_f32 v[32:35], v36, v97, v[32:35]
	v_mfma_f32_16x16x4_f32 v[60:63], v36, v98, v[60:63]
	s_waitcnt vmcnt(37)
	v_mfma_f32_16x16x4_f32 v[4:7], v37, v107, v[4:7]
	v_mfma_f32_16x16x4_f32 v[8:11], v37, v100, v[8:11]
	v_mfma_f32_16x16x4_f32 v[12:15], v37, v101, v[12:15]
	v_mfma_f32_16x16x4_f32 v[16:19], v37, v102, v[16:19]
	v_mfma_f32_16x16x4_f32 v[20:23], v37, v103, v[20:23]
	v_mfma_f32_16x16x4_f32 v[24:27], v37, v104, v[24:27]
	v_mfma_f32_16x16x4_f32 v[28:31], v37, v105, v[28:31]
	v_mfma_f32_16x16x4_f32 v[32:35], v37, v106, v[32:35]
	s_waitcnt vmcnt(36)
	v_mfma_f32_16x16x4_f32 v[60:63], v37, v108, v[60:63]
	v_lshl_add_u64 v[36:37], v[2:3], 0, s[26:27]
	global_load_dword v91, v[36:37], off offset:64 nt
	global_load_dword v92, v[36:37], off offset:128 nt
	global_load_dword v93, v[36:37], off offset:192 nt
	global_load_dword v94, v[36:37], off offset:256 nt
	global_load_dword v95, v[36:37], off offset:320 nt
	global_load_dword v96, v[36:37], off offset:384 nt
	global_load_dword v97, v[36:37], off offset:448 nt
	global_load_dword v98, v[36:37], off offset:512 nt
	v_lshl_add_u64 v[36:37], v[2:3], 0, s[28:29]
	global_load_dword v99, v[64:65], off nt
	global_load_dword v100, v[36:37], off offset:64 nt
	global_load_dword v101, v[36:37], off offset:128 nt
	global_load_dword v102, v[36:37], off offset:192 nt
	global_load_dword v103, v[36:37], off offset:256 nt
	global_load_dword v104, v[36:37], off offset:320 nt
	global_load_dword v105, v[36:37], off offset:384 nt
	global_load_dword v106, v[36:37], off offset:448 nt
	global_load_dword v107, v[66:67], off nt
	global_load_dword v108, v[36:37], off offset:512 nt
	ds_read2_b32 v[36:37], v52 offset1:48
	v_add_co_u32_e64 v64, s[12:13], s12, v2
	s_waitcnt vmcnt(45) lgkmcnt(0)
; #define MV_LOAD(w, g8) do { _Pragma("unroll") for (int qq = 0; qq < 2; ++qq) { const GAS float* rp_ = Wu + (size_t)(8 * (g8) + 4 * qq) * DMODW; \
;             _Pragma("unroll") for (int j = 0; j < 9; ++j) w[9 * qq + j] = (rp_ + 16 * j)[loff]; } asm volatile("" ::: "memory"); } while (0)
; #define MV_COMP(w, g8) do { _Pragma("unroll") for (int qq = 0; qq < 2; ++qq) { const float a_ = svw[48 * (2 * (g8) + qq)]; \
;             _Pragma("unroll") for (int j = 0; j < 9; ++j) acc[j] = __builtin_amdgcn_mfma_f32_16x16x4f32(a_, w[9 * qq + j], acc[j], 0, 0, 0); } } while (0)
; __device__ __forceinline__ void p0_modvec(const Params& p, LAS unsigned char* lds, int tid, int lane, int wave) {
;     ...
;         float wa[18], wb[18], wc[18];
;         MV_LOAD(wa, 0); MV_LOAD(wb, 1); MV_LOAD(wc, 2);
;         MV_COMP(wa, 0); MV_LOAD(wa, 3);
;         MV_COMP(wb, 1); MV_LOAD(wb, 4);
;         MV_COMP(wc, 2); MV_LOAD(wc, 5);
;         MV_COMP(wa, 3); MV_LOAD(wa, 6);
;         MV_COMP(wb, 4); MV_LOAD(wb, 7);
;         MV_COMP(wc, 5); MV_LOAD(wc, 8);
;         MV_COMP(wa, 6); MV_LOAD(wa, 9);
;         MV_COMP(wb, 7); MV_LOAD(wb, 10);
;         MV_COMP(wc, 8); MV_LOAD(wc, 11);
;         MV_COMP(wa, 9); MV_LOAD(wa, 12);
;         MV_COMP(wb, 10); MV_LOAD(wb, 13);
;         MV_COMP(wc, 11); MV_LOAD(wc, 14);
;         MV_COMP(wa, 12); MV_LOAD(wa, 15);
;         MV_COMP(wb, 13); MV_LOAD(wb, 16);
;         MV_COMP(wc, 14); MV_LOAD(wc, 17);
;         MV_COMP(wa, 15); MV_LOAD(wa, 18);
;         MV_COMP(wb, 16); MV_LOAD(wb, 19);
;         MV_COMP(wc, 17); MV_LOAD(wc, 20);
;         MV_COMP(wa, 18); MV_LOAD(wa, 21);
;         MV_COMP(wb, 19); MV_LOAD(wb, 22);
;         MV_COMP(wc, 20); MV_LOAD(wc, 23);
;         MV_COMP(wa, 21); MV_LOAD(wa, 24);
;         MV_COMP(wb, 22); MV_LOAD(wb, 25);
;         MV_COMP(wc, 23); MV_LOAD(wc, 26);
;         MV_COMP(wa, 24); MV_LOAD(wa, 27);
;         MV_COMP(wb, 25); MV_LOAD(wb, 28);
;         MV_COMP(wc, 26); MV_LOAD(wc, 29);
;         MV_COMP(wa, 27); MV_LOAD(wa, 30);
;         MV_COMP(wb, 28); MV_LOAD(wb, 31);
;         MV_COMP(wc, 29);
;         MV_COMP(wa, 30);
;         MV_COMP(wb, 31);
	v_mfma_f32_16x16x4_f32 v[4:7], v36, v112, v[4:7]
	v_addc_co_u32_e64 v65, s[12:13], 0, v3, s[12:13]
	s_mov_b32 s12, 0xf78000
	s_nop 0
	v_add_co_u32_e64 v66, s[12:13], s12, v2
	s_nop 1
	v_addc_co_u32_e64 v67, s[12:13], 0, v3, s[12:13]
	v_mfma_f32_16x16x4_f32 v[8:11], v36, v68, v[8:11]
	s_mov_b32 s12, 0xfc0000
	v_mfma_f32_16x16x4_f32 v[12:15], v36, v69, v[12:15]
	v_mfma_f32_16x16x4_f32 v[16:19], v36, v70, v[16:19]
	v_mfma_f32_16x16x4_f32 v[20:23], v36, v71, v[20:23]
	v_mfma_f32_16x16x4_f32 v[24:27], v36, v72, v[24:27]
	v_mfma_f32_16x16x4_f32 v[28:31], v36, v109, v[28:31]
	v_mfma_f32_16x16x4_f32 v[32:35], v36, v110, v[32:35]
	v_mfma_f32_16x16x4_f32 v[60:63], v36, v111, v[60:63]
	s_waitcnt vmcnt(37)
	v_mfma_f32_16x16x4_f32 v[4:7], v37, v120, v[4:7]
	v_mfma_f32_16x16x4_f32 v[8:11], v37, v113, v[8:11]
	v_mfma_f32_16x16x4_f32 v[12:15], v37, v114, v[12:15]
	v_mfma_f32_16x16x4_f32 v[16:19], v37, v115, v[16:19]
	v_mfma_f32_16x16x4_f32 v[20:23], v37, v116, v[20:23]
	v_mfma_f32_16x16x4_f32 v[24:27], v37, v117, v[24:27]
	v_mfma_f32_16x16x4_f32 v[28:31], v37, v118, v[28:31]
	v_mfma_f32_16x16x4_f32 v[32:35], v37, v119, v[32:35]
	s_waitcnt vmcnt(36)
	v_mfma_f32_16x16x4_f32 v[60:63], v37, v121, v[60:63]
	v_lshl_add_u64 v[36:37], v[2:3], 0, s[30:31]
	global_load_dword v68, v[36:37], off offset:64 nt
	global_load_dword v69, v[36:37], off offset:128 nt
	global_load_dword v70, v[36:37], off offset:192 nt
	global_load_dword v71, v[36:37], off offset:256 nt
	global_load_dword v72, v[36:37], off offset:320 nt
	global_load_dword v109, v[36:37], off offset:384 nt
	global_load_dword v110, v[36:37], off offset:448 nt
	global_load_dword v111, v[36:37], off offset:512 nt
	v_lshl_add_u64 v[36:37], v[2:3], 0, s[34:35]
	global_load_dword v112, v[64:65], off nt
	global_load_dword v113, v[36:37], off offset:64 nt
	global_load_dword v114, v[36:37], off offset:128 nt
	global_load_dword v115, v[36:37], off offset:192 nt
	global_load_dword v116, v[36:37], off offset:256 nt
	global_load_dword v117, v[36:37], off offset:320 nt
	global_load_dword v118, v[36:37], off offset:384 nt
	global_load_dword v119, v[36:37], off offset:448 nt
	global_load_dword v120, v[66:67], off nt
	global_load_dword v121, v[36:37], off offset:512 nt
	ds_read2_b32 v[36:37], v52 offset0:96 offset1:144
	v_add_co_u32_e64 v64, s[12:13], s12, v2
	s_waitcnt vmcnt(45) lgkmcnt(0)
	v_mfma_f32_16x16x4_f32 v[4:7], v36, v81, v[4:7]
	v_addc_co_u32_e64 v65, s[12:13], 0, v3, s[12:13]
	s_mov_b32 s12, 0x1008000
	s_nop 0
	v_add_co_u32_e64 v66, s[12:13], s12, v2
	s_nop 1
	v_addc_co_u32_e64 v67, s[12:13], 0, v3, s[12:13]
	v_mfma_f32_16x16x4_f32 v[8:11], v36, v73, v[8:11]
	s_mov_b32 s12, 0x1050000
	v_mfma_f32_16x16x4_f32 v[12:15], v36, v74, v[12:15]
	v_mfma_f32_16x16x4_f32 v[16:19], v36, v75, v[16:19]
	v_mfma_f32_16x16x4_f32 v[20:23], v36, v76, v[20:23]
	v_mfma_f32_16x16x4_f32 v[24:27], v36, v77, v[24:27]
	v_mfma_f32_16x16x4_f32 v[28:31], v36, v78, v[28:31]
	v_mfma_f32_16x16x4_f32 v[32:35], v36, v79, v[32:35]
	v_mfma_f32_16x16x4_f32 v[60:63], v36, v80, v[60:63]
	s_waitcnt vmcnt(37)
	v_mfma_f32_16x16x4_f32 v[4:7], v37, v89, v[4:7]
	v_mfma_f32_16x16x4_f32 v[8:11], v37, v82, v[8:11]
	v_mfma_f32_16x16x4_f32 v[12:15], v37, v83, v[12:15]
	v_mfma_f32_16x16x4_f32 v[16:19], v37, v84, v[16:19]
	v_mfma_f32_16x16x4_f32 v[20:23], v37, v85, v[20:23]
	v_mfma_f32_16x16x4_f32 v[24:27], v37, v86, v[24:27]
	v_mfma_f32_16x16x4_f32 v[28:31], v37, v87, v[28:31]
	v_mfma_f32_16x16x4_f32 v[32:35], v37, v88, v[32:35]
	s_waitcnt vmcnt(36)
	v_mfma_f32_16x16x4_f32 v[60:63], v37, v90, v[60:63]
	v_lshl_add_u64 v[36:37], v[2:3], 0, s[36:37]
	global_load_dword v73, v[36:37], off offset:64 nt
	global_load_dword v74, v[36:37], off offset:128 nt
	global_load_dword v75, v[36:37], off offset:192 nt
	global_load_dword v76, v[36:37], off offset:256 nt
	global_load_dword v77, v[36:37], off offset:320 nt
	global_load_dword v78, v[36:37], off offset:384 nt
	global_load_dword v79, v[36:37], off offset:448 nt
	global_load_dword v80, v[36:37], off offset:512 nt
	v_lshl_add_u64 v[36:37], v[2:3], 0, s[38:39]
	global_load_dword v81, v[64:65], off nt
	global_load_dword v82, v[36:37], off offset:64 nt
	global_load_dword v83, v[36:37], off offset:128 nt
	global_load_dword v84, v[36:37], off offset:192 nt
	global_load_dword v85, v[36:37], off offset:256 nt
	global_load_dword v86, v[36:37], off offset:320 nt
	global_load_dword v87, v[36:37], off offset:384 nt
	global_load_dword v88, v[36:37], off offset:448 nt
	global_load_dword v89, v[66:67], off nt
	global_load_dword v90, v[36:37], off offset:512 nt
	ds_read2_b32 v[36:37], v52 offset0:192 offset1:240
	v_add_co_u32_e64 v64, s[12:13], s12, v2
	s_waitcnt vmcnt(45) lgkmcnt(0)
	v_mfma_f32_16x16x4_f32 v[4:7], v36, v99, v[4:7]
	v_addc_co_u32_e64 v65, s[12:13], 0, v3, s[12:13]
	s_mov_b32 s12, 0x1098000
	s_nop 0
	v_add_co_u32_e64 v66, s[12:13], s12, v2
	s_nop 1
	v_addc_co_u32_e64 v67, s[12:13], 0, v3, s[12:13]
	v_mfma_f32_16x16x4_f32 v[8:11], v36, v91, v[8:11]
	s_mov_b32 s12, 0x10e0000
	v_mfma_f32_16x16x4_f32 v[12:15], v36, v92, v[12:15]
	v_mfma_f32_16x16x4_f32 v[16:19], v36, v93, v[16:19]
	v_mfma_f32_16x16x4_f32 v[20:23], v36, v94, v[20:23]
	v_mfma_f32_16x16x4_f32 v[24:27], v36, v95, v[24:27]
	v_mfma_f32_16x16x4_f32 v[28:31], v36, v96, v[28:31]
	v_mfma_f32_16x16x4_f32 v[32:35], v36, v97, v[32:35]
	v_mfma_f32_16x16x4_f32 v[60:63], v36, v98, v[60:63]
	s_waitcnt vmcnt(37)
	v_mfma_f32_16x16x4_f32 v[4:7], v37, v107, v[4:7]
	v_mfma_f32_16x16x4_f32 v[8:11], v37, v100, v[8:11]
	v_mfma_f32_16x16x4_f32 v[12:15], v37, v101, v[12:15]
	v_mfma_f32_16x16x4_f32 v[16:19], v37, v102, v[16:19]
	v_mfma_f32_16x16x4_f32 v[20:23], v37, v103, v[20:23]
	v_mfma_f32_16x16x4_f32 v[24:27], v37, v104, v[24:27]
	v_mfma_f32_16x16x4_f32 v[28:31], v37, v105, v[28:31]
	v_mfma_f32_16x16x4_f32 v[32:35], v37, v106, v[32:35]
	s_waitcnt vmcnt(36)
; #define MV_LOAD(w, g8) do { _Pragma("unroll") for (int qq = 0; qq < 2; ++qq) { const GAS float* rp_ = Wu + (size_t)(8 * (g8) + 4 * qq) * DMODW; \
;             _Pragma("unroll") for (int j = 0; j < 9; ++j) w[9 * qq + j] = (rp_ + 16 * j)[loff]; } asm volatile("" ::: "memory"); } while (0)
; #define MV_COMP(w, g8) do { _Pragma("unroll") for (int qq = 0; qq < 2; ++qq) { const float a_ = svw[48 * (2 * (g8) + qq)]; \
;             _Pragma("unroll") for (int j = 0; j < 9; ++j) acc[j] = __builtin_amdgcn_mfma_f32_16x16x4f32(a_, w[9 * qq + j], acc[j], 0, 0, 0); } } while (0)
; __device__ __forceinline__ void p0_modvec(const Params& p, LAS unsigned char* lds, int tid, int lane, int wave) {
;     ...
;         float wa[18], wb[18], wc[18];
;         MV_LOAD(wa, 0); MV_LOAD(wb, 1); MV_LOAD(wc, 2);
;         MV_COMP(wa, 0); MV_LOAD(wa, 3);
;         MV_COMP(wb, 1); MV_LOAD(wb, 4);
;         MV_COMP(wc, 2); MV_LOAD(wc, 5);
;         MV_COMP(wa, 3); MV_LOAD(wa, 6);
;         MV_COMP(wb, 4); MV_LOAD(wb, 7);
;         MV_COMP(wc, 5); MV_LOAD(wc, 8);
;         MV_COMP(wa, 6); MV_LOAD(wa, 9);
;         MV_COMP(wb, 7); MV_LOAD(wb, 10);
;         MV_COMP(wc, 8); MV_LOAD(wc, 11);
;         MV_COMP(wa, 9); MV_LOAD(wa, 12);
;         MV_COMP(wb, 10); MV_LOAD(wb, 13);
;         MV_COMP(wc, 11); MV_LOAD(wc, 14);
;         MV_COMP(wa, 12); MV_LOAD(wa, 15);
;         MV_COMP(wb, 13); MV_LOAD(wb, 16);
;         MV_COMP(wc, 14); MV_LOAD(wc, 17);
;         MV_COMP(wa, 15); MV_LOAD(wa, 18);
;         MV_COMP(wb, 16); MV_LOAD(wb, 19);
;         MV_COMP(wc, 17); MV_LOAD(wc, 20);
;         MV_COMP(wa, 18); MV_LOAD(wa, 21);
;         MV_COMP(wb, 19); MV_LOAD(wb, 22);
;         MV_COMP(wc, 20); MV_LOAD(wc, 23);
;         MV_COMP(wa, 21); MV_LOAD(wa, 24);
;         MV_COMP(wb, 22); MV_LOAD(wb, 25);
;         MV_COMP(wc, 23); MV_LOAD(wc, 26);
;         MV_COMP(wa, 24); MV_LOAD(wa, 27);
;         MV_COMP(wb, 25); MV_LOAD(wb, 28);
;         MV_COMP(wc, 26); MV_LOAD(wc, 29);
;         MV_COMP(wa, 27); MV_LOAD(wa, 30);
;         MV_COMP(wb, 28); MV_LOAD(wb, 31);
;         MV_COMP(wc, 29);
;         MV_COMP(wa, 30);
;         MV_COMP(wb, 31);
	v_mfma_f32_16x16x4_f32 v[60:63], v37, v108, v[60:63]
	v_lshl_add_u64 v[36:37], v[2:3], 0, s[40:41]
	global_load_dword v91, v[36:37], off offset:64 nt
	global_load_dword v92, v[36:37], off offset:128 nt
	global_load_dword v93, v[36:37], off offset:192 nt
	global_load_dword v94, v[36:37], off offset:256 nt
	global_load_dword v95, v[36:37], off offset:320 nt
	global_load_dword v96, v[36:37], off offset:384 nt
	global_load_dword v97, v[36:37], off offset:448 nt
	global_load_dword v98, v[36:37], off offset:512 nt
	v_lshl_add_u64 v[36:37], v[2:3], 0, s[42:43]
	global_load_dword v99, v[64:65], off nt
	global_load_dword v100, v[36:37], off offset:64 nt
	global_load_dword v101, v[36:37], off offset:128 nt
	global_load_dword v102, v[36:37], off offset:192 nt
	global_load_dword v103, v[36:37], off offset:256 nt
	global_load_dword v104, v[36:37], off offset:320 nt
	global_load_dword v105, v[36:37], off offset:384 nt
	global_load_dword v106, v[36:37], off offset:448 nt
	global_load_dword v107, v[66:67], off nt
	global_load_dword v108, v[36:37], off offset:512 nt
	ds_read2_b32 v[36:37], v53 offset0:32 offset1:80
	v_add_co_u32_e64 v64, s[12:13], s12, v2
	s_waitcnt vmcnt(45) lgkmcnt(0)
	v_mfma_f32_16x16x4_f32 v[4:7], v36, v112, v[4:7]
	v_addc_co_u32_e64 v65, s[12:13], 0, v3, s[12:13]
	s_mov_b32 s12, 0x1128000
	s_nop 0
	v_add_co_u32_e64 v66, s[12:13], s12, v2
	s_nop 1
	v_addc_co_u32_e64 v67, s[12:13], 0, v3, s[12:13]
	v_mfma_f32_16x16x4_f32 v[8:11], v36, v68, v[8:11]
	s_mov_b32 s12, 0x1170000
	v_mfma_f32_16x16x4_f32 v[12:15], v36, v69, v[12:15]
	v_mfma_f32_16x16x4_f32 v[16:19], v36, v70, v[16:19]
	v_mfma_f32_16x16x4_f32 v[20:23], v36, v71, v[20:23]
	v_mfma_f32_16x16x4_f32 v[24:27], v36, v72, v[24:27]
	v_mfma_f32_16x16x4_f32 v[28:31], v36, v109, v[28:31]
	v_mfma_f32_16x16x4_f32 v[32:35], v36, v110, v[32:35]
	v_mfma_f32_16x16x4_f32 v[60:63], v36, v111, v[60:63]
	s_waitcnt vmcnt(37)
	v_mfma_f32_16x16x4_f32 v[4:7], v37, v120, v[4:7]
	v_mfma_f32_16x16x4_f32 v[8:11], v37, v113, v[8:11]
	v_mfma_f32_16x16x4_f32 v[12:15], v37, v114, v[12:15]
	v_mfma_f32_16x16x4_f32 v[16:19], v37, v115, v[16:19]
	v_mfma_f32_16x16x4_f32 v[20:23], v37, v116, v[20:23]
	v_mfma_f32_16x16x4_f32 v[24:27], v37, v117, v[24:27]
	v_mfma_f32_16x16x4_f32 v[28:31], v37, v118, v[28:31]
	v_mfma_f32_16x16x4_f32 v[32:35], v37, v119, v[32:35]
	s_waitcnt vmcnt(36)
	v_mfma_f32_16x16x4_f32 v[60:63], v37, v121, v[60:63]
	v_lshl_add_u64 v[36:37], v[2:3], 0, s[44:45]
	global_load_dword v68, v[36:37], off offset:64 nt
	global_load_dword v69, v[36:37], off offset:128 nt
	global_load_dword v70, v[36:37], off offset:192 nt
	global_load_dword v71, v[36:37], off offset:256 nt
	global_load_dword v72, v[36:37], off offset:320 nt
	global_load_dword v109, v[36:37], off offset:384 nt
	global_load_dword v110, v[36:37], off offset:448 nt
	global_load_dword v111, v[36:37], off offset:512 nt
	v_lshl_add_u64 v[36:37], v[2:3], 0, s[46:47]
	global_load_dword v112, v[64:65], off nt
	global_load_dword v113, v[36:37], off offset:64 nt
	global_load_dword v114, v[36:37], off offset:128 nt
	global_load_dword v115, v[36:37], off offset:192 nt
	global_load_dword v116, v[36:37], off offset:256 nt
	global_load_dword v117, v[36:37], off offset:320 nt
	global_load_dword v118, v[36:37], off offset:384 nt
	global_load_dword v119, v[36:37], off offset:448 nt
	global_load_dword v120, v[66:67], off nt
	global_load_dword v121, v[36:37], off offset:512 nt
	ds_read2_b32 v[36:37], v53 offset0:128 offset1:176
	v_add_co_u32_e64 v64, s[12:13], s12, v2
	s_waitcnt vmcnt(45) lgkmcnt(0)
	v_mfma_f32_16x16x4_f32 v[4:7], v36, v81, v[4:7]
	v_addc_co_u32_e64 v65, s[12:13], 0, v3, s[12:13]
	s_mov_b32 s12, 0x11b8000
	s_nop 0
	v_add_co_u32_e64 v66, s[12:13], s12, v2
	s_nop 1
	v_addc_co_u32_e64 v67, s[12:13], 0, v3, s[12:13]
	v_mfma_f32_16x16x4_f32 v[8:11], v36, v73, v[8:11]
	v_mfma_f32_16x16x4_f32 v[12:15], v36, v74, v[12:15]
	v_mfma_f32_16x16x4_f32 v[16:19], v36, v75, v[16:19]
	v_mfma_f32_16x16x4_f32 v[20:23], v36, v76, v[20:23]
	v_mfma_f32_16x16x4_f32 v[24:27], v36, v77, v[24:27]
	v_mfma_f32_16x16x4_f32 v[28:31], v36, v78, v[28:31]
	v_mfma_f32_16x16x4_f32 v[32:35], v36, v79, v[32:35]
	v_mfma_f32_16x16x4_f32 v[60:63], v36, v80, v[60:63]
	s_waitcnt vmcnt(37)
	v_mfma_f32_16x16x4_f32 v[4:7], v37, v89, v[4:7]
	v_mfma_f32_16x16x4_f32 v[8:11], v37, v82, v[8:11]
	v_mfma_f32_16x16x4_f32 v[12:15], v37, v83, v[12:15]
	v_mfma_f32_16x16x4_f32 v[16:19], v37, v84, v[16:19]
	v_mfma_f32_16x16x4_f32 v[20:23], v37, v85, v[20:23]
	v_mfma_f32_16x16x4_f32 v[24:27], v37, v86, v[24:27]
	v_mfma_f32_16x16x4_f32 v[28:31], v37, v87, v[28:31]
	v_mfma_f32_16x16x4_f32 v[32:35], v37, v88, v[32:35]
	s_waitcnt vmcnt(36)
; #define MV_LOAD(w, g8) do { _Pragma("unroll") for (int qq = 0; qq < 2; ++qq) { const GAS float* rp_ = Wu + (size_t)(8 * (g8) + 4 * qq) * DMODW; \
;             _Pragma("unroll") for (int j = 0; j < 9; ++j) w[9 * qq + j] = (rp_ + 16 * j)[loff]; } asm volatile("" ::: "memory"); } while (0)
; #define MV_COMP(w, g8) do { _Pragma("unroll") for (int qq = 0; qq < 2; ++qq) { const float a_ = svw[48 * (2 * (g8) + qq)]; \
;             _Pragma("unroll") for (int j = 0; j < 9; ++j) acc[j] = __builtin_amdgcn_mfma_f32_16x16x4f32(a_, w[9 * qq + j], acc[j], 0, 0, 0); } } while (0)
; __device__ __forceinline__ void p0_modvec(const Params& p, LAS unsigned char* lds, int tid, int lane, int wave) {
;     ...
;         float wa[18], wb[18], wc[18];
;         MV_LOAD(wa, 0); MV_LOAD(wb, 1); MV_LOAD(wc, 2);
;         MV_COMP(wa, 0); MV_LOAD(wa, 3);
;         MV_COMP(wb, 1); MV_LOAD(wb, 4);
;         MV_COMP(wc, 2); MV_LOAD(wc, 5);
;         MV_COMP(wa, 3); MV_LOAD(wa, 6);
;         MV_COMP(wb, 4); MV_LOAD(wb, 7);
;         MV_COMP(wc, 5); MV_LOAD(wc, 8);
;         MV_COMP(wa, 6); MV_LOAD(wa, 9);
;         MV_COMP(wb, 7); MV_LOAD(wb, 10);
;         MV_COMP(wc, 8); MV_LOAD(wc, 11);
;         MV_COMP(wa, 9); MV_LOAD(wa, 12);
;         MV_COMP(wb, 10); MV_LOAD(wb, 13);
;         MV_COMP(wc, 11); MV_LOAD(wc, 14);
;         MV_COMP(wa, 12); MV_LOAD(wa, 15);
;         MV_COMP(wb, 13); MV_LOAD(wb, 16);
;         MV_COMP(wc, 14); MV_LOAD(wc, 17);
;         MV_COMP(wa, 15); MV_LOAD(wa, 18);
;         MV_COMP(wb, 16); MV_LOAD(wb, 19);
;         MV_COMP(wc, 17); MV_LOAD(wc, 20);
;         MV_COMP(wa, 18); MV_LOAD(wa, 21);
;         MV_COMP(wb, 19); MV_LOAD(wb, 22);
;         MV_COMP(wc, 20); MV_LOAD(wc, 23);
;         MV_COMP(wa, 21); MV_LOAD(wa, 24);
;         MV_COMP(wb, 22); MV_LOAD(wb, 25);
;         MV_COMP(wc, 23); MV_LOAD(wc, 26);
;         MV_COMP(wa, 24); MV_LOAD(wa, 27);
;         MV_COMP(wb, 25); MV_LOAD(wb, 28);
;         MV_COMP(wc, 26); MV_LOAD(wc, 29);
;         MV_COMP(wa, 27); MV_LOAD(wa, 30);
;         MV_COMP(wb, 28); MV_LOAD(wb, 31);
;         MV_COMP(wc, 29);
;         MV_COMP(wa, 30);
;         MV_COMP(wb, 31);
;     ...
;         for (int j = 0; j < 9; ++j)
; #pragma unroll
;             for (int e = 0; e < 4; ++e) { const int r = 4 * lk + e; if (r < 9) red[(wave * 9 + r) * UC + 16 * j + ln] = acc[j][e]; }
	v_mfma_f32_16x16x4_f32 v[60:63], v37, v90, v[60:63]
	v_lshl_add_u64 v[36:37], v[2:3], 0, s[48:49]
	global_load_dword v73, v[36:37], off offset:64 nt
	global_load_dword v74, v[36:37], off offset:128 nt
	global_load_dword v75, v[36:37], off offset:192 nt
	global_load_dword v78, v[36:37], off offset:256 nt
	global_load_dword v79, v[36:37], off offset:320 nt
	global_load_dword v80, v[36:37], off offset:384 nt
	global_load_dword v81, v[36:37], off offset:448 nt
	global_load_dword v82, v[36:37], off offset:512 nt
	v_lshl_add_u64 v[2:3], v[2:3], 0, s[50:51]
	global_load_dword v83, v[64:65], off nt
	global_load_dword v84, v[2:3], off offset:64 nt
	global_load_dword v85, v[2:3], off offset:128 nt
	global_load_dword v86, v[2:3], off offset:192 nt
	global_load_dword v87, v[2:3], off offset:256 nt
	global_load_dword v88, v[2:3], off offset:320 nt
	global_load_dword v89, v[2:3], off offset:384 nt
	global_load_dword v90, v[2:3], off offset:448 nt
	global_load_dword v122, v[66:67], off nt
	global_load_dword v123, v[2:3], off offset:512 nt
	ds_read2_b32 v[64:65], v54 offset0:96 offset1:144
	ds_read2_b32 v[76:77], v55 offset0:160 offset1:208
	s_waitcnt vmcnt(45) lgkmcnt(1)
	v_mfma_f32_16x16x4_f32 v[2:5], v64, v99, v[4:7]
	v_mfma_f32_16x16x4_f32 v[6:9], v64, v91, v[8:11]
	v_mfma_f32_16x16x4_f32 v[10:13], v64, v92, v[12:15]
	v_mfma_f32_16x16x4_f32 v[14:17], v64, v93, v[16:19]
	v_mfma_f32_16x16x4_f32 v[18:21], v64, v94, v[20:23]
	v_mfma_f32_16x16x4_f32 v[22:25], v64, v95, v[24:27]
	v_mfma_f32_16x16x4_f32 v[26:29], v64, v96, v[28:31]
	v_mfma_f32_16x16x4_f32 v[30:33], v64, v97, v[32:35]
	v_mfma_f32_16x16x4_f32 v[34:37], v64, v98, v[60:63]
	ds_read2_b32 v[60:61], v55 offset0:64 offset1:112
	s_waitcnt vmcnt(37)
	v_mfma_f32_16x16x4_f32 v[2:5], v65, v107, v[2:5]
	v_mfma_f32_16x16x4_f32 v[6:9], v65, v100, v[6:9]
	v_mfma_f32_16x16x4_f32 v[10:13], v65, v101, v[10:13]
	v_mfma_f32_16x16x4_f32 v[14:17], v65, v102, v[14:17]
	v_mfma_f32_16x16x4_f32 v[18:21], v65, v103, v[18:21]
	v_mfma_f32_16x16x4_f32 v[22:25], v65, v104, v[22:25]
	v_mfma_f32_16x16x4_f32 v[26:29], v65, v105, v[26:29]
	v_mfma_f32_16x16x4_f32 v[30:33], v65, v106, v[30:33]
	s_waitcnt vmcnt(36)
	v_mfma_f32_16x16x4_f32 v[34:37], v65, v108, v[34:37]
	s_waitcnt vmcnt(27) lgkmcnt(0)
	v_mfma_f32_16x16x4_f32 v[2:5], v60, v112, v[2:5]
	v_mfma_f32_16x16x4_f32 v[6:9], v60, v68, v[6:9]
	v_mfma_f32_16x16x4_f32 v[10:13], v60, v69, v[10:13]
	v_mfma_f32_16x16x4_f32 v[14:17], v60, v70, v[14:17]
	v_mfma_f32_16x16x4_f32 v[18:21], v60, v71, v[18:21]
	v_mfma_f32_16x16x4_f32 v[22:25], v60, v72, v[22:25]
	v_mfma_f32_16x16x4_f32 v[26:29], v60, v109, v[26:29]
	v_mfma_f32_16x16x4_f32 v[30:33], v60, v110, v[30:33]
	v_mfma_f32_16x16x4_f32 v[34:37], v60, v111, v[34:37]
	s_waitcnt vmcnt(19)
	v_mfma_f32_16x16x4_f32 v[2:5], v61, v120, v[2:5]
	v_mfma_f32_16x16x4_f32 v[6:9], v61, v113, v[6:9]
	v_mfma_f32_16x16x4_f32 v[10:13], v61, v114, v[10:13]
	v_mfma_f32_16x16x4_f32 v[14:17], v61, v115, v[14:17]
	v_mfma_f32_16x16x4_f32 v[18:21], v61, v116, v[18:21]
	v_mfma_f32_16x16x4_f32 v[22:25], v61, v117, v[22:25]
	v_mfma_f32_16x16x4_f32 v[26:29], v61, v118, v[26:29]
	v_mfma_f32_16x16x4_f32 v[30:33], v61, v119, v[30:33]
	s_waitcnt vmcnt(18)
	v_mfma_f32_16x16x4_f32 v[34:37], v61, v121, v[34:37]
	s_waitcnt vmcnt(9)
	v_mfma_f32_16x16x4_f32 v[2:5], v76, v83, v[2:5]
	v_mfma_f32_16x16x4_f32 v[6:9], v76, v73, v[6:9]
	v_mfma_f32_16x16x4_f32 v[10:13], v76, v74, v[10:13]
	v_mfma_f32_16x16x4_f32 v[14:17], v76, v75, v[14:17]
	v_mfma_f32_16x16x4_f32 v[18:21], v76, v78, v[18:21]
	v_mfma_f32_16x16x4_f32 v[60:63], v76, v79, v[22:25]
	v_mfma_f32_16x16x4_f32 v[64:67], v76, v80, v[26:29]
	v_mfma_f32_16x16x4_f32 v[68:71], v76, v81, v[30:33]
	v_mfma_f32_16x16x4_f32 v[72:75], v76, v82, v[34:37]
	s_waitcnt vmcnt(1)
	v_mfma_f32_16x16x4_f32 v[34:37], v77, v122, v[2:5]
	v_mfma_f32_16x16x4_f32 v[30:33], v77, v84, v[6:9]
	v_mfma_f32_16x16x4_f32 v[26:29], v77, v85, v[10:13]
	v_mfma_f32_16x16x4_f32 v[22:25], v77, v86, v[14:17]
	v_mfma_f32_16x16x4_f32 v[18:21], v77, v87, v[18:21]
	v_mfma_f32_16x16x4_f32 v[14:17], v77, v88, v[60:63]
	v_mfma_f32_16x16x4_f32 v[10:13], v77, v89, v[64:67]
	v_mfma_f32_16x16x4_f32 v[6:9], v77, v90, v[68:71]
	s_waitcnt vmcnt(0)
	v_mfma_f32_16x16x4_f32 v[2:5], v77, v123, v[72:75]
	s_and_saveexec_b64 s[12:13], vcc
	s_cbranch_execz .LBB0_52
	ds_write_b32 v56, v34
	s_or_b64 exec, exec, s[12:13]
	s_and_saveexec_b64 s[12:13], s[10:11]
	s_cbranch_execnz .LBB0_53

; __device__ __forceinline__ void p0_modvec(const Params& p, LAS unsigned char* lds, int tid, int lane, int wave) {
;     ...
;         for (int o = t2; o < 9 * UC; o += 512) {
;             const int r = o / UC, cn = o - r * UC; float s = 0.f;
; #pragma unroll
;             for (int w = 0; w < 8; ++w) s += red[(w * 9 + r) * UC + cn];
;             MOD[((size_t)l * 9 + r) * DMODW + col0 + cn] = s + p.in[IN_BMOD][(size_t)l * DMODW + col0 + cn];
;         }
.LBB0_90:
	s_mov_b32 s12, 0x38e38e39
	v_mul_hi_i32 v4, v2, s12
	v_lshrrev_b32_e32 v5, 31, v4
	v_ashrrev_i32_e32 v4, 5, v4
	v_add_u32_e32 v4, v4, v5
	s_movk_i32 s12, 0xff70
	v_mad_u64_u32 v[6:7], s[12:13], v4, s12, v[2:3]
	v_ashrrev_i32_e32 v7, 31, v6
	v_lshlrev_b64 v[6:7], 2, v[6:7]
	v_lshl_add_u64 v[8:9], s[52:53], 0, v[6:7]
	global_load_dword v10, v[8:9], off nt
	s_movk_i32 s12, 0x30f
	v_ashrrev_i32_e32 v5, 31, v4
	ds_read_b32 v11, v3
	ds_read_b32 v12, v3 offset:5184
	ds_read_b32 v13, v3 offset:10368
	ds_read_b32 v14, v3 offset:15552
	ds_read_b32 v15, v3 offset:20736
	ds_read_b32 v16, v3 offset:25920
	ds_read_b32 v17, v3 offset:31104
	ds_read_b32 v18, v3 offset:36288
	v_mov_b64_e32 v[8:9], s[56:57]
	v_cmp_lt_i32_e64 s[12:13], s12, v2
	v_lshl_add_u64 v[4:5], s[58:59], 0, v[4:5]
	s_or_b64 s[60:61], s[12:13], s[60:61]
	s_waitcnt lgkmcnt(7)
	v_add_f32_e32 v11, 0, v11
	v_mad_u64_u32 v[8:9], s[12:13], v4, s64, v[8:9]
	s_waitcnt lgkmcnt(6)
	v_add_f32_e32 v11, v11, v12
	v_mov_b32_e32 v4, v9
	s_waitcnt lgkmcnt(5)
	v_add_f32_e32 v9, v11, v13
	v_mad_u64_u32 v[4:5], s[12:13], v5, s64, v[4:5]
	s_waitcnt lgkmcnt(4)
	v_add_f32_e32 v5, v9, v14
	v_mov_b32_e32 v9, v4
	s_waitcnt lgkmcnt(3)
	v_add_f32_e32 v11, v5, v15
	v_lshl_add_u64 v[4:5], v[8:9], 0, v[6:7]
	s_waitcnt lgkmcnt(2)
	v_add_f32_e32 v6, v11, v16
	s_waitcnt lgkmcnt(1)
	v_add_f32_e32 v6, v6, v17
	v_add_u32_e32 v19, 0x200, v2
	s_waitcnt lgkmcnt(0)
	v_add_f32_e32 v6, v6, v18
	v_add_u32_e32 v3, 0x800, v3
	v_mov_b32_e32 v2, v19
	s_waitcnt vmcnt(0)
	v_add_f32_e32 v6, v6, v10
	global_store_dword v[4:5], v6, off
	s_andn2_b64 exec, exec, s[60:61]
	s_cbranch_execnz .LBB0_90
	s_branch .LBB0_15
